# prompt-unit prologues: conv / Q / key-bias loads waited with a counted ladder (each value right before its first use) instead of one vmcnt(0)
# baseline (speedup 1.0000x reference)
; #define LAS __attribute__((address_space(3)))
; __device__ __forceinline__ void conv_load(ConvRegs& c, const Args& a, size_t rowq, int col, int lane) {
; #pragma unroll
;     for (int i = 0; i < 4; ++i) { const size_t grow = rowq + i * 8 + (lane >> 3);
;         c.k[i] = *(const u32x4*)((const bf16*)(a.ws + WS_K) + grow * D + col + (lane & 7) * 8); c.v[i] = *(const u32x4*)((const bf16*)(a.ws + WS_V) + grow * D + col + (lane & 7) * 8); }
; }
; __device__ __forceinline__ void prompt_unit_sb(const Args& a, int l, int b, int h, int qb, LAS unsigned char* lds) {
;     int tid_ = threadIdx.x; asm volatile("" : "+v"(tid_));
;     const int tid = tid_, lane = tid & 63, r32 = lane & 31, hi = lane >> 5, wid = __builtin_amdgcn_readfirstlane(tid >> 6);
;     f16x8 T00, T01; make_tri(T00, T01, r32, hi);
;     const int q0 = qb * 256, jb = q0 / 64, jd = jb + (wid >> 1);
;     const int col = W + h * HD;
;     const size_t rowb = (size_t)b * T;
;     const bf16* Kh = (const bf16*)(a.ws + WS_K) + rowb * D + col; const bf16* Vh = (const bf16*)(a.ws + WS_V) + rowb * D + col;
;     const unsigned lds0 = (unsigned)(uintptr_t)lds;
;     const bf16* ksrc = Kh + (size_t)lane * D + wid * 8;
;     const bf16* vsrc = Vh + (size_t)(16 * (wid & 3) + (lane >> 2)) * D + (wid >> 2) * 32 + (lane & 3) * 8;
;     ...
;     ATT_DMA(jb + 3); ATT_DMA(jb + 2); ATT_DMA(jb + 1); ATT_DMA(jb);
;     if (jb >= 4) { ATT_DMA(jb - 1); ATT_DMA(jb - 2); ATT_DMA(jb - 3); }
;     bf16x8 qr[4];
;     { const bf16* Qw = (const bf16*)(a.ws + WS_Q) + (rowb + q0 + wid * 32 + r32) * D + col;
; #pragma unroll
;       for (int d0 = 0; d0 < 4; ++d0) qr[d0] = *(const bf16x8*)(Qw + d0 * 16 + hi * 8); }
;     const lds_cptr vp0 = (lds_cptr)lds + B_V + ((lane >> 4) & 1) * 32 + (lane & 3) * 8 + (4 * hi + ((lane & 15) >> 2)) * 64;
;     const int qlim = 32 * (wid & 1) + r32;
;     LAS float* wsf = (LAS float*)(lds + B_WSF) + wid * 64;
;     LAS unsigned* flags = (LAS unsigned*)(lds + B_FLAG);
;     FoxState st; st.m = 0.f; st.l = 0.f; st.mq = (bf16x8){}; st.o[0] = (f32x16){}; st.o[1] = (f32x16){};
;     float R = 0.f; bool done = false;
;     { ConvRegs cv; conv_load(cv, a, rowb + q0 + wid * 32, col, lane); conv_store<1>(cv, a, l, h, rowb + q0 + wid * 32, lane); }
.LBB0_267:
	s_lshl_b32 s0, s4, 8
	s_ashr_i32 s4, s6, 7
	s_ashr_i32 s1, s0, 31
	v_lshrrev_b32_e32 v54, 5, v2
	s_add_u32 s0, s0, s7
	v_and_b32_e32 v169, 31, v19
	v_lshlrev_b32_e32 v55, 2, v54
	s_addc_u32 s1, s1, 0
	s_lshl_b32 s6, s82, 5
	v_cmp_lt_u32_e32 vcc, v55, v169
	v_or_b32_e32 v56, 16, v55
	s_ashr_i32 s7, s6, 31
	v_cndmask_b32_e64 v14, v181, 0, vcc
	v_cmp_lt_u32_e32 vcc, v56, v169
	v_or_b32_e32 v58, 1, v55
	s_add_u32 s78, s0, s6
	v_cndmask_b32_e64 v26, v181, 0, vcc
	v_or_b32_e32 v57, 2, v55
	v_cmp_lt_u32_e32 vcc, v58, v169
	s_addc_u32 s79, s1, s7
	v_or_b32_e32 v60, 17, v55
	v_cndmask_b32_e64 v15, v181, 0, vcc
	v_cmp_lt_u32_e32 vcc, v57, v169
	v_or_b32_e32 v160, s78, v169
	v_mov_b32_e32 v161, s79
	v_readlane_b32 s0, v242, 22
	v_cndmask_b32_e64 v16, v181, 0, vcc
	v_or_b32_e32 v59, 18, v55
	v_cmp_lt_u32_e32 vcc, v60, v169
	v_lshlrev_b64 v[6:7], 11, v[160:161]
	v_readlane_b32 s1, v242, 23
	v_cndmask_b32_e64 v27, v181, 0, vcc
	v_cmp_lt_u32_e32 vcc, v59, v169
	v_or_b32_e32 v62, 3, v55
	v_lshl_add_u64 v[6:7], s[0:1], 0, v[6:7]
	s_lshl_b32 s0, s5, 1
	s_mov_b32 s1, s87
	v_lshrrev_b32_e32 v1, 3, v2
	v_cndmask_b32_e64 v20, v181, 0, vcc
	v_or_b32_e32 v61, 8, v55
	v_cmp_lt_u32_e32 vcc, v62, v169
	v_lshl_add_u64 v[6:7], v[6:7], 0, s[0:1]
	v_lshlrev_b32_e32 v4, 4, v54
	v_or_b32_e32 v160, s78, v1
	v_cndmask_b32_e64 v17, v181, 0, vcc
	v_cmp_lt_u32_e32 vcc, v61, v169
	v_or_b32_e32 v64, 19, v55
	v_lshl_add_u64 v[24:25], v[6:7], 0, v[4:5]
	v_lshlrev_b32_e32 v4, 3, v2
	v_lshlrev_b64 v[166:167], 11, v[160:161]
	v_readlane_b32 s8, v242, 20
	v_cndmask_b32_e64 v21, v181, 0, vcc
	v_or_b32_e32 v63, 24, v55
	v_cmp_lt_u32_e32 vcc, v64, v169
	v_and_b32_e32 v168, 56, v4
	v_lshl_add_u64 v[6:7], s[94:95], 0, v[166:167]
	v_readlane_b32 s9, v242, 21
	v_cndmask_b32_e64 v22, v181, 0, vcc
	v_cmp_lt_u32_e32 vcc, v63, v169
	v_or_b32_e32 v65, 10, v55
	v_lshl_add_u64 v[6:7], v[6:7], 0, s[0:1]
	v_mov_b32_e32 v4, v168
	v_lshl_add_u64 v[10:11], s[8:9], 0, v[166:167]
	v_cndmask_b32_e64 v23, v181, 0, vcc
	v_or_b32_e32 v66, 9, v55
	v_lshl_add_u64 v[6:7], v[6:7], 0, v[4:5]
	v_cmp_lt_u32_e32 vcc, v65, v169
	v_lshl_add_u64 v[10:11], v[10:11], 0, s[0:1]
	global_load_dwordx2 v[8:9], v[6:7], off offset:1088
	global_load_dwordx2 v[6:7], v[6:7], off offset:1024
	v_cndmask_b32_e64 v28, v181, 0, vcc
	v_cmp_lt_u32_e32 vcc, v66, v169
	v_or_b32_e32 v67, 26, v55
	v_lshl_add_u64 v[10:11], v[10:11], 0, v[4:5]
	v_cndmask_b32_e64 v29, v181, 0, vcc
	v_or_b32_e32 v68, 25, v55
	global_load_dwordx2 v[12:13], v[10:11], off offset:1088
	global_load_dwordx2 v[10:11], v[10:11], off offset:1024
	v_cmp_lt_u32_e32 vcc, v67, v169
	v_or_b32_e32 v69, 11, v55
	v_or_b32_e32 v44, 0x4000, v166
	v_cndmask_b32_e64 v30, v181, 0, vcc
	v_cmp_lt_u32_e32 vcc, v68, v169
	v_mov_b32_e32 v45, v167
	v_or_b32_e32 v70, 27, v55
	v_cndmask_b32_e64 v31, v181, 0, vcc
	v_cmp_lt_u32_e32 vcc, v69, v169
	v_pack_b32_f16 v116, v14, v15
	v_lshl_add_u64 v[14:15], s[94:95], 0, v[44:45]
	v_cndmask_b32_e64 v32, v181, 0, vcc
	v_cmp_lt_u32_e32 vcc, v70, v169
	v_pack_b32_f16 v118, v21, v29
	v_lshl_add_u64 v[14:15], v[14:15], 0, s[0:1]
	v_cndmask_b32_e64 v21, v181, 0, vcc
	v_lshl_add_u64 v[14:15], v[14:15], 0, v[4:5]
	v_pack_b32_f16 v121, v20, v22
	v_pack_b32_f16 v123, v30, v21
	v_lshl_add_u64 v[20:21], s[8:9], 0, v[44:45]
	v_pack_b32_f16 v117, v16, v17
	global_load_dwordx2 v[16:17], v[14:15], off offset:1088
	global_load_dwordx2 v[14:15], v[14:15], off offset:1024
	v_lshl_add_u64 v[20:21], v[20:21], 0, s[0:1]
	v_lshl_add_u64 v[20:21], v[20:21], 0, v[4:5]
	v_pack_b32_f16 v122, v23, v31
	global_load_dwordx2 v[22:23], v[20:21], off offset:1088
	global_load_dwordx2 v[20:21], v[20:21], off offset:1024
	s_nop 0
	global_load_dwordx4 v[124:127], v[24:25], off offset:1024
	global_load_dwordx4 v[128:131], v[24:25], off offset:1056
	global_load_dwordx4 v[132:135], v[24:25], off offset:1088
	global_load_dwordx4 v[136:139], v[24:25], off offset:1120
	v_lshlrev_b32_e32 v24, 1, v19
	v_and_b32_e32 v24, 32, v24
	s_add_i32 s7, 0, 0x10000
	v_or_b32_e32 v46, 0x8000, v166
	v_mov_b32_e32 v47, v167
	v_add3_u32 v3, s7, v24, v3
	v_lshl_add_u64 v[24:25], s[94:95], 0, v[46:47]
	v_lshlrev_b32_e32 v29, 4, v19
	v_pack_b32_f16 v119, v28, v32
	v_lshlrev_b32_e32 v28, 8, v54
	v_lshl_add_u64 v[24:25], v[24:25], 0, s[0:1]
	v_and_b32_e32 v29, 0xc0, v29
	v_lshl_add_u64 v[24:25], v[24:25], 0, v[4:5]
	v_add3_u32 v170, v3, v28, v29
	v_lshl_add_u64 v[28:29], s[8:9], 0, v[46:47]
	v_pack_b32_f16 v120, v26, v27
	global_load_dwordx2 v[26:27], v[24:25], off offset:1088
	global_load_dwordx2 v[24:25], v[24:25], off offset:1024
	v_lshl_add_u64 v[28:29], v[28:29], 0, s[0:1]
	v_lshl_add_u64 v[28:29], v[28:29], 0, v[4:5]
	global_load_dwordx2 v[30:31], v[28:29], off offset:1088
	global_load_dwordx2 v[28:29], v[28:29], off offset:1024
	v_or_b32_e32 v48, 0xc000, v166
	v_mov_b32_e32 v49, v167
	v_lshl_add_u64 v[32:33], s[94:95], 0, v[48:49]
	v_lshl_add_u64 v[34:35], s[8:9], 0, v[48:49]
	v_lshl_add_u64 v[32:33], v[32:33], 0, s[0:1]
	v_lshl_add_u64 v[34:35], v[34:35], 0, s[0:1]
	v_lshl_add_u64 v[32:33], v[32:33], 0, v[4:5]
	v_lshl_add_u64 v[36:37], v[34:35], 0, v[4:5]
	global_load_dwordx2 v[34:35], v[32:33], off offset:1088
	global_load_dwordx2 v[32:33], v[32:33], off offset:1024
	s_nop 0
	global_load_dwordx2 v[38:39], v[36:37], off offset:1088
	global_load_dwordx2 v[36:37], v[36:37], off offset:1024
	v_and_or_b32 v3, s6, 32, v169
	v_readlane_b32 s6, v242, 24
	v_readlane_b32 s7, v242, 25
	s_lshl_b32 s92, s5, 2
	s_mov_b32 s93, s87
	v_lshl_add_u64 v[40:41], s[6:7], 0, v[166:167]
	v_readlane_b32 s8, v242, 26
	v_lshl_add_u64 v[40:41], v[40:41], 0, s[92:93]
	v_lshlrev_b32_e32 v4, 1, v168
	v_readlane_b32 s9, v242, 27
	v_lshl_add_u64 v[50:51], v[40:41], 0, v[4:5]
	v_lshlrev_b32_e32 v171, 10, v54
	v_lshl_add_u64 v[40:41], s[8:9], 0, v[166:167]
	v_lshl_add_u64 v[40:41], v[40:41], 0, s[92:93]
	v_lshl_add_u64 v[52:53], v[40:41], 0, v[4:5]
	s_lshl_b32 s1, s82, 2

; __device__ __forceinline__ float bflo(unsigned w) { return __uint_as_float(w << 16); }
; __device__ __forceinline__ float bfhi(unsigned w) { return __uint_as_float(w & 0xffff0000u); }
; #define ATT_WAIT_BAR_N(N) asm volatile("s_waitcnt vmcnt(" #N ") lgkmcnt(0)\n\ts_barrier" ::: "memory")
; template <int TYPE>
; __device__ __forceinline__ void conv_store(const ConvRegs& c, const Args& a, int l, int h, size_t rowq, int lane) {
; #pragma unroll
;     for (int i = 0; i < 4; ++i) { const size_t grow = rowq + i * 8 + (lane >> 3);
;         float* ko = a.out + (TYPE == 0 ? O_FKP : O_SKP) + ((size_t)l * MP + grow) * W + h * HD + (lane & 7) * 8;
;         float* vo = a.out + (TYPE == 0 ? O_FVP : O_SVP) + ((size_t)l * MP + grow) * W + h * HD + (lane & 7) * 8;
;         const u32x4 kw = c.k[i], vw = c.v[i];
;         __builtin_nontemporal_store((f32x4){bflo(kw.x), bfhi(kw.x), bflo(kw.y), bfhi(kw.y)}, (f32x4*)ko); __builtin_nontemporal_store((f32x4){bflo(kw.z), bfhi(kw.z), bflo(kw.w), bfhi(kw.w)}, (f32x4*)(ko + 4));
;         __builtin_nontemporal_store((f32x4){bflo(vw.x), bfhi(vw.x), bflo(vw.y), bfhi(vw.y)}, (f32x4*)vo); __builtin_nontemporal_store((f32x4){bflo(vw.z), bfhi(vw.z), bflo(vw.w), bfhi(vw.w)}, (f32x4*)(vo + 4)); }
; }
; __device__ __forceinline__ void prompt_unit_sb(const Args& a, int l, int b, int h, int qb, LAS unsigned char* lds) {
;     ...
;     FoxState st; st.m = 0.f; st.l = 0.f; st.mq = (bf16x8){}; st.o[0] = (f32x16){}; st.o[1] = (f32x16){};
;     float R = 0.f; bool done = false;
;     { ConvRegs cv; conv_load(cv, a, rowb + q0 + wid * 32, col, lane); conv_store<1>(cv, a, l, h, rowb + q0 + wid * 32, lane); }
;     for (int it = 0; ; ++it) {
;         const int need = jb - it;
;         if (need >= 3) ATT_WAIT_BAR_N(6); else if (need == 2) ATT_WAIT_BAR_N(4); else if (need == 1) ATT_WAIT_BAR_N(2); else ATT_WAIT_BAR_N(0);
	s_waitcnt vmcnt(18)
	v_lshlrev_b32_e32 v40, 16, v6
	v_and_b32_e32 v41, 0xffff0000, v6
	v_lshlrev_b32_e32 v42, 16, v7
	v_and_b32_e32 v43, 0xffff0000, v7
	v_lshlrev_b32_e32 v6, 16, v8
	v_and_b32_e32 v7, 0xffff0000, v8
	v_lshlrev_b32_e32 v8, 16, v9
	v_and_b32_e32 v9, 0xffff0000, v9
	global_store_dwordx4 v[50:51], v[6:9], off offset:128
	global_store_dwordx4 v[50:51], v[40:43], off
	s_add_i32 s1, s1, 0
	s_waitcnt vmcnt(18)
	v_lshlrev_b32_e32 v6, 16, v10
	v_and_b32_e32 v7, 0xffff0000, v10
	v_lshlrev_b32_e32 v8, 16, v11
	v_and_b32_e32 v9, 0xffff0000, v11
	global_store_dwordx4 v[52:53], v[6:9], off
	v_cmp_lt_u32_e64 s[10:11], v58, v3
	v_cmp_lt_u32_e64 s[14:15], v57, v3
	v_lshlrev_b32_e32 v6, 16, v12
	v_and_b32_e32 v7, 0xffff0000, v12
	v_lshlrev_b32_e32 v8, 16, v13
	v_and_b32_e32 v9, 0xffff0000, v13
	global_store_dwordx4 v[52:53], v[6:9], off offset:128
	v_cmp_lt_u32_e64 s[18:19], v62, v3
	v_cmp_lt_u32_e64 s[22:23], v61, v3
	v_lshl_add_u64 v[6:7], s[6:7], 0, v[44:45]
	v_lshl_add_u64 v[6:7], v[6:7], 0, s[92:93]
	v_lshl_add_u64 v[10:11], v[6:7], 0, v[4:5]
	v_lshl_add_u64 v[6:7], s[8:9], 0, v[44:45]
	v_lshl_add_u64 v[6:7], v[6:7], 0, s[92:93]
	v_lshl_add_u64 v[12:13], v[6:7], 0, v[4:5]
	s_waitcnt vmcnt(18)
	v_lshlrev_b32_e32 v6, 16, v14
	v_and_b32_e32 v7, 0xffff0000, v14
	v_lshlrev_b32_e32 v8, 16, v15
	v_and_b32_e32 v9, 0xffff0000, v15
	global_store_dwordx4 v[10:11], v[6:9], off
	v_cmp_lt_u32_e64 s[26:27], v66, v3
	v_cmp_lt_u32_e64 s[30:31], v65, v3
	v_lshlrev_b32_e32 v6, 16, v16
	v_and_b32_e32 v7, 0xffff0000, v16
	v_lshlrev_b32_e32 v8, 16, v17
	v_and_b32_e32 v9, 0xffff0000, v17
	global_store_dwordx4 v[10:11], v[6:9], off offset:128
	v_mov_b32_e32 v16, v5
	v_mov_b32_e32 v17, v5
	s_waitcnt vmcnt(18)
	v_lshlrev_b32_e32 v6, 16, v20
	v_and_b32_e32 v7, 0xffff0000, v20
	v_lshlrev_b32_e32 v8, 16, v21
	v_and_b32_e32 v9, 0xffff0000, v21
	global_store_dwordx4 v[12:13], v[6:9], off
	v_and_or_b32 v20, v183, 64, v169
	v_cmp_lt_u32_e64 s[36:37], v69, v3
	v_lshlrev_b32_e32 v6, 16, v22
	v_and_b32_e32 v7, 0xffff0000, v22
	v_lshlrev_b32_e32 v8, 16, v23
	v_and_b32_e32 v9, 0xffff0000, v23
	global_store_dwordx4 v[12:13], v[6:9], off offset:128
	v_cmp_lt_u32_e64 s[40:41], v56, v3
	v_cmp_lt_u32_e64 s[44:45], v60, v3
	v_lshl_add_u64 v[6:7], s[6:7], 0, v[46:47]
	v_lshl_add_u64 v[6:7], v[6:7], 0, s[92:93]
	v_lshl_add_u64 v[10:11], v[6:7], 0, v[4:5]
	v_lshl_add_u64 v[6:7], s[8:9], 0, v[46:47]
	v_lshl_add_u64 v[6:7], v[6:7], 0, s[92:93]
	v_lshl_add_u64 v[12:13], v[6:7], 0, v[4:5]
	s_waitcnt vmcnt(14)
	v_lshlrev_b32_e32 v6, 16, v24
	v_and_b32_e32 v7, 0xffff0000, v24
	v_lshlrev_b32_e32 v8, 16, v25
	v_and_b32_e32 v9, 0xffff0000, v25
	global_store_dwordx4 v[10:11], v[6:9], off
	v_cmp_lt_u32_e64 s[48:49], v59, v3
	v_cmp_lt_u32_e64 s[52:53], v64, v3
	v_lshlrev_b32_e32 v6, 16, v26
	v_and_b32_e32 v7, 0xffff0000, v26
	v_lshlrev_b32_e32 v8, 16, v27
	v_and_b32_e32 v9, 0xffff0000, v27
	global_store_dwordx4 v[10:11], v[6:9], off offset:128
	v_cmp_lt_u32_e64 s[56:57], v63, v3
	v_cmp_lt_u32_e64 s[60:61], v68, v3
	s_waitcnt vmcnt(14)
	v_lshlrev_b32_e32 v6, 16, v28
	v_and_b32_e32 v7, 0xffff0000, v28
	v_lshlrev_b32_e32 v8, 16, v29
	v_and_b32_e32 v9, 0xffff0000, v29
	global_store_dwordx4 v[12:13], v[6:9], off
	v_cmp_lt_u32_e64 s[64:65], v67, v3
	v_cmp_lt_u32_e64 s[68:69], v70, v3
	v_lshlrev_b32_e32 v6, 16, v30
	v_and_b32_e32 v7, 0xffff0000, v30
	v_lshlrev_b32_e32 v8, 16, v31
	v_and_b32_e32 v9, 0xffff0000, v31
	global_store_dwordx4 v[12:13], v[6:9], off offset:128
	v_cmp_eq_u32_e64 s[72:73], 0, v2
	s_lshl_b32 s5, s3, 15
	v_lshl_add_u64 v[6:7], s[6:7], 0, v[48:49]
	v_lshl_add_u64 v[6:7], v[6:7], 0, s[92:93]
	v_lshl_add_u64 v[10:11], v[6:7], 0, v[4:5]
	v_lshl_add_u64 v[6:7], s[8:9], 0, v[48:49]
	v_lshl_add_u64 v[6:7], v[6:7], 0, s[92:93]
	v_lshl_add_u64 v[12:13], v[6:7], 0, v[4:5]
	v_lshlrev_b32_e32 v4, 4, v169
	v_add3_u32 v172, 0, v171, v4
	v_or_b32_e32 v4, 32, v55
	v_cmp_lt_u32_e64 s[8:9], v4, v3
	v_or_b32_e32 v4, 33, v55
	v_cmp_lt_u32_e64 s[12:13], v4, v3
	v_or_b32_e32 v4, 34, v55
	v_cmp_lt_u32_e64 s[16:17], v4, v3
	v_or_b32_e32 v4, 35, v55
	v_cmp_lt_u32_e64 s[20:21], v4, v3
	v_or_b32_e32 v4, 40, v55
	v_cmp_lt_u32_e64 s[24:25], v4, v3
	v_or_b32_e32 v4, 41, v55
	v_cmp_lt_u32_e64 s[28:29], v4, v3
	v_or_b32_e32 v4, 42, v55
	v_cmp_lt_u32_e64 s[34:35], v4, v3
	v_or_b32_e32 v4, 43, v55
	v_cmp_lt_u32_e64 s[38:39], v4, v3
	v_or_b32_e32 v4, 48, v55
	v_cmp_lt_u32_e64 s[42:43], v4, v3
	v_or_b32_e32 v4, 49, v55
	v_cmp_lt_u32_e64 s[46:47], v4, v3
	v_or_b32_e32 v4, 50, v55
	v_cmp_lt_u32_e64 s[50:51], v4, v3
	v_or_b32_e32 v4, 51, v55
	s_waitcnt vmcnt(14)
	v_lshlrev_b32_e32 v6, 16, v32
	v_and_b32_e32 v7, 0xffff0000, v32
	v_lshlrev_b32_e32 v8, 16, v33
	v_and_b32_e32 v9, 0xffff0000, v33
	v_cmp_lt_u32_e64 s[54:55], v4, v3
	v_or_b32_e32 v4, 56, v55
	global_store_dwordx4 v[10:11], v[6:9], off
	v_cmp_lt_u32_e64 s[58:59], v4, v3
	v_or_b32_e32 v4, 57, v55
	v_lshlrev_b32_e32 v6, 16, v34
	v_and_b32_e32 v7, 0xffff0000, v34
	v_lshlrev_b32_e32 v8, 16, v35
	v_and_b32_e32 v9, 0xffff0000, v35
	global_store_dwordx4 v[10:11], v[6:9], off offset:128
	v_cmp_lt_u32_e64 s[62:63], v4, v3
	v_or_b32_e32 v4, 58, v55
	s_waitcnt vmcnt(14)
	v_lshlrev_b32_e32 v6, 16, v36
	v_and_b32_e32 v7, 0xffff0000, v36
	v_lshlrev_b32_e32 v8, 16, v37
	v_and_b32_e32 v9, 0xffff0000, v37
	global_store_dwordx4 v[12:13], v[6:9], off
	v_cmp_lt_u32_e64 s[66:67], v4, v3
	v_or_b32_e32 v4, 59, v55
	v_lshlrev_b32_e32 v6, 16, v38
	v_and_b32_e32 v7, 0xffff0000, v38
	v_lshlrev_b32_e32 v8, 16, v39
	v_and_b32_e32 v9, 0xffff0000, v39
	global_store_dwordx4 v[12:13], v[6:9], off offset:128
	v_cmp_lt_u32_e64 s[6:7], v55, v3
	v_cmp_lt_u32_e64 s[70:71], v4, v3
	s_lshl_b32 s3, s3, 2
	v_mov_b32_e32 v2, v5
	v_mov_b32_e32 v3, v5
	v_mov_b32_e32 v4, v5
	v_mov_b32_e32 v6, v5
	v_mov_b32_e32 v7, v5
	v_mov_b32_e32 v8, v5
	v_mov_b32_e32 v9, v5
	v_mov_b32_e32 v10, v5
	v_mov_b32_e32 v11, v5
	v_mov_b32_e32 v12, v5
	v_mov_b32_e32 v13, v5
	v_mov_b32_e32 v14, v5
	v_mov_b32_e32 v15, v5
	v_lshlrev_b32_e32 v173, 2, v20
	v_mov_b64_e32 v[34:35], v[16:17]
	v_mov_b64_e32 v[50:51], v[16:17]
	s_add_i32 s1, s1, 0x20c00
	s_mov_b32 s85, 0
	s_lshl_b32 s93, s4, 13
	s_sub_i32 s94, 0x30000, s5
	s_sub_i32 s95, s4, s3
	s_sub_i32 s33, 0, s3
	v_mov_b32_e32 v52, 0
	s_mov_b64 s[74:75], 0
	v_mov_b64_e32 v[32:33], v[14:15]
	v_mov_b64_e32 v[30:31], v[12:13]
	v_mov_b64_e32 v[28:29], v[10:11]
	v_mov_b64_e32 v[26:27], v[8:9]
	v_mov_b64_e32 v[24:25], v[6:7]
	v_mov_b64_e32 v[22:23], v[4:5]
	v_mov_b64_e32 v[20:21], v[2:3]
	v_mov_b64_e32 v[48:49], v[14:15]
	v_mov_b64_e32 v[46:47], v[12:13]
	v_mov_b64_e32 v[44:45], v[10:11]
	v_mov_b64_e32 v[42:43], v[8:9]
	v_mov_b64_e32 v[40:41], v[6:7]
	v_mov_b64_e32 v[38:39], v[4:5]
	v_mov_b64_e32 v[36:37], v[2:3]
	s_mov_b32 s3, 28
	s_add_i32 s89, s33, s3
	s_waitcnt lgkmcnt(0)
	s_barrier
	s_branch .LBB0_281

; #define LAS __attribute__((address_space(3)))
; __device__ __forceinline__ unsigned cvtpk(float lo, float hi) { f32x2 v = {lo, hi}; bf16x2_t b = __builtin_convertvector(v, bf16x2_t); return __builtin_bit_cast(unsigned, b); }
; __device__ __forceinline__ void prompt_unit_fox(const Args& a, int l, int b, int h, int qb, LAS unsigned char* lds) {
;     int tid_ = threadIdx.x; asm volatile("" : "+v"(tid_));
;     const int tid = tid_, lane = tid & 63, r32 = lane & 31, hi = lane >> 5, wid = __builtin_amdgcn_readfirstlane(tid >> 6);
;     const int q0 = qb * 256, NP = (q0 + 256) / 128, jd = q0 / 64 + (wid >> 1), jpd = jd >> 1;
;     const bool lateB = wid >= 4;
;     const int col = h * HD;
;     const size_t rowb = (size_t)b * T;
;     const bf16* Kh = (const bf16*)(a.ws + WS_K) + rowb * D + col; const bf16* Vh = (const bf16*)(a.ws + WS_V) + rowb * D + col;
;     const unsigned lds0 = (unsigned)(uintptr_t)lds;
;     const bf16* ksrc = Kh + (size_t)lane * D + wid * 8;
;     const bf16* vsrc = Vh + (size_t)(16 * (wid & 3) + (lane >> 2)) * D + (wid >> 2) * 32 + (lane & 3) * 8;
;     ...
;     ATT_DMA2(NP - 1, 0);
;     { const int idx = tid * 4; if (idx < q0 + 256) { const f32x4 c = *(const f32x4*)((const float*)(a.ws + WS_CKP) + (size_t)(b * 8 + h) * T + idx); *(LAS f32x4*)(lds + F_CK + idx * 4) = c;
; #pragma unroll
;         for (int e = 0; e < 4; ++e) { const float h1 = bf_hi_part(c[e]), r1 = c[e] - h1, h2 = bf_hi_part(r1), r2 = r1 - h2; ((LAS u32x2*)(lds + F_AUG))[idx + e] = (u32x2){cvtpk(h1, h2), cvtpk(r2, -1.0f)}; } } }
;     bf16x8 qr[4];
;     { const bf16* Qw = (const bf16*)(a.ws + WS_Q) + (rowb + q0 + wid * 32 + r32) * D + col;
; #pragma unroll
;       for (int d0 = 0; d0 < 4; ++d0) qr[d0] = *(const bf16x8*)(Qw + d0 * 16 + hi * 8); }
;     const lds_cptr vp0 = (lds_cptr)lds + F_V + ((lane >> 4) & 1) * 32 + (lane & 3) * 8 + (4 * hi + ((lane & 15) >> 2)) * 64;
;     const int ql = 32 * (wid & 1) + r32, qlim = ql + 1;
;     LAS float* wsf = (LAS float*)(lds + F_WSF) + wid * 64;
;     FoxState st; st.m = 0.f; st.l = 0.f; st.mq = (bf16x8){}; st.o[0] = (f32x16){}; st.o[1] = (f32x16){};
;     PairP pp; bool pending = false;
; #pragma unroll
;     for (int i = 0; i < 8; ++i) pp.w[i] = (u32x4){0u, 0u, 0u, 0u};
;     { ConvRegs cv; conv_load(cv, a, rowb + q0 + wid * 32, col, lane); conv_store<0>(cv, a, l, h, rowb + q0 + wid * 32, lane); }
.LBB0_311:
	s_or_b64 exec, exec, s[0:1]
	s_lshl_b32 s0, s6, 2
	s_ashr_i32 s1, s3, 7
	s_add_i32 s1, s1, s0
	s_ashr_i32 s89, s1, 1
	s_cmp_lt_i32 s77, 4
	s_cselect_b64 s[92:93], -1, 0
	s_lshl_b32 s0, s5, 11
	s_lshl_b32 s5, s77, 5
	s_or_b32 s0, s7, s0
	s_ashr_i32 s1, s5, 31
	s_add_u32 s91, s5, s0
	v_and_b32_e32 v175, 31, v19
	s_addc_u32 s0, s1, 0
	v_or_b32_e32 v168, s91, v175
	v_mov_b32_e32 v169, s0
	v_lshrrev_b32_e32 v1, 3, v20
	v_lshlrev_b64 v[2:3], 11, v[168:169]
	v_or_b32_e32 v168, s91, v1
	v_lshlrev_b32_e32 v4, 3, v20
	v_lshlrev_b64 v[170:171], 11, v[168:169]
	s_lshl_b32 s74, s4, 1
	s_mov_b32 s75, s87
	v_and_b32_e32 v174, 56, v4
	v_lshl_add_u64 v[8:9], s[94:95], 0, v[170:171]
	v_lshl_add_u64 v[8:9], v[8:9], 0, s[74:75]
	v_mov_b32_e32 v4, v174
	v_readlane_b32 s6, v242, 20
	v_lshl_add_u64 v[8:9], v[8:9], 0, v[4:5]
	v_readlane_b32 s7, v242, 21
	global_load_dwordx2 v[24:25], v[8:9], off offset:64
	global_load_dwordx2 v[22:23], v[8:9], off
	v_or_b32_e32 v58, 0x4000, v170
	v_lshl_add_u64 v[8:9], s[6:7], 0, v[170:171]
	v_lshl_add_u64 v[8:9], v[8:9], 0, s[74:75]
	v_lshl_add_u64 v[8:9], v[8:9], 0, v[4:5]
	v_mov_b32_e32 v59, v171
	global_load_dwordx2 v[28:29], v[8:9], off offset:64
	global_load_dwordx2 v[26:27], v[8:9], off
	v_lshl_add_u64 v[8:9], s[94:95], 0, v[58:59]
	v_lshl_add_u64 v[8:9], v[8:9], 0, s[74:75]
	v_lshl_add_u64 v[8:9], v[8:9], 0, v[4:5]
	global_load_dwordx2 v[32:33], v[8:9], off offset:64
	global_load_dwordx2 v[30:31], v[8:9], off
	v_lshl_add_u64 v[8:9], s[6:7], 0, v[58:59]
	v_lshrrev_b32_e32 v21, 5, v20
	v_lshl_add_u64 v[8:9], v[8:9], 0, s[74:75]
	v_lshlrev_b32_e32 v7, 1, v19
	v_lshrrev_b32_e32 v10, 2, v19
	v_lshlrev_b32_e32 v66, 2, v21
	v_lshl_add_u64 v[8:9], v[8:9], 0, v[4:5]
	v_and_b32_e32 v7, 32, v7
	global_load_dwordx2 v[36:37], v[8:9], off offset:64
	global_load_dwordx2 v[34:35], v[8:9], off
	v_and_or_b32 v8, v10, 3, v66
	v_add_u32_e32 v7, 0, v7
	v_lshlrev_b32_e32 v8, 6, v8
	v_or_b32_e32 v60, 0x8000, v170
	v_mov_b32_e32 v61, v171
	v_add3_u32 v180, v7, v6, v8
	v_lshl_add_u64 v[6:7], s[94:95], 0, v[60:61]
	v_and_or_b32 v67, s5, 32, v175
	s_and_b32 s5, s3, 0x3fffffc0
	v_lshl_add_u64 v[6:7], v[6:7], 0, s[74:75]
	v_writelane_b32 v237, s0, 11
	s_lshl_b32 s0, s4, 2
	s_lshl_b32 s4, s5, 2
	v_lshl_add_u64 v[6:7], v[6:7], 0, v[4:5]
	v_lshl_add_u64 v[10:11], s[6:7], 0, v[60:61]
	s_add_i32 s78, s4, 0
	v_readlane_b32 s4, v242, 22
	global_load_dwordx2 v[40:41], v[6:7], off offset:64
	global_load_dwordx2 v[38:39], v[6:7], off
	v_lshl_add_u64 v[10:11], v[10:11], 0, s[74:75]
	v_readlane_b32 s5, v242, 23
	v_lshl_add_u64 v[10:11], v[10:11], 0, v[4:5]
	v_readlane_b32 s8, v242, 45
	v_lshl_add_u64 v[2:3], s[4:5], 0, v[2:3]
	v_readlane_b32 s4, v242, 43
	global_load_dwordx2 v[44:45], v[10:11], off offset:64
	global_load_dwordx2 v[42:43], v[10:11], off
	v_mov_b32_e32 v173, v5
	v_lshlrev_b32_e32 v172, 4, v21
	v_lshl_add_u64 v[2:3], v[2:3], 0, s[74:75]
	v_or_b32_e32 v62, 0xc000, v170
	v_mov_b32_e32 v63, v171
	v_readlane_b32 s5, v242, 44
	v_readlane_b32 s9, v242, 46
	s_mov_b32 s1, s87
	v_lshl_add_u64 v[6:7], s[4:5], 0, v[170:171]
	v_lshl_add_u64 v[8:9], s[8:9], 0, v[170:171]
	v_lshl_add_u64 v[2:3], v[2:3], 0, v[172:173]
	v_lshl_add_u64 v[46:47], s[94:95], 0, v[62:63]
	v_lshl_add_u64 v[48:49], s[6:7], 0, v[62:63]
	v_lshl_add_u64 v[54:55], v[6:7], 0, s[0:1]
	v_lshl_add_u64 v[56:57], v[8:9], 0, s[0:1]
	global_load_dwordx4 v[6:9], v[2:3], off
	global_load_dwordx4 v[10:13], v[2:3], off offset:32
	global_load_dwordx4 v[14:17], v[2:3], off offset:64
	global_load_dwordx4 v[116:119], v[2:3], off offset:96
	v_lshl_add_u64 v[2:3], v[46:47], 0, s[74:75]
	v_lshl_add_u64 v[46:47], v[48:49], 0, s[74:75]
	v_lshl_add_u64 v[2:3], v[2:3], 0, v[4:5]
	v_lshl_add_u64 v[50:51], v[46:47], 0, v[4:5]
	global_load_dwordx2 v[48:49], v[2:3], off offset:64
	global_load_dwordx2 v[46:47], v[2:3], off
	s_nop 0
	global_load_dwordx2 v[52:53], v[50:51], off offset:64
	global_load_dwordx2 v[50:51], v[50:51], off
	v_lshlrev_b32_e32 v4, 1, v174
	v_lshl_add_u64 v[2:3], v[54:55], 0, v[4:5]
	v_lshl_add_u64 v[64:65], v[56:57], 0, v[4:5]
	s_add_i32 s78, s78, 0x1a000
	v_cmp_lt_u32_e64 s[12:13], v66, v67
	v_cmp_gt_u32_e64 s[6:7], 32, v20
	v_lshlrev_b32_e32 v173, 10, v21
	v_lshlrev_b32_e32 v188, 4, v175
	v_cndmask_b32_e64 v122, 0, v185, s[6:7]
	v_cndmask_b32_e64 v121, 0, -1.0, s[6:7]
	v_mov_b32_e32 v120, v5
	v_mov_b32_e32 v123, v5
	v_lshl_add_u32 v182, v175, 2, s78
	v_mov_b32_e32 v156, v5

; #define LAS __attribute__((address_space(3)))
; __device__ __forceinline__ float bflo(unsigned w) { return __uint_as_float(w << 16); }
; __device__ __forceinline__ float bfhi(unsigned w) { return __uint_as_float(w & 0xffff0000u); }
; __device__ __forceinline__ unsigned cvtpk(float lo, float hi) { f32x2 v = {lo, hi}; bf16x2_t b = __builtin_convertvector(v, bf16x2_t); return __builtin_bit_cast(unsigned, b); }
; __device__ __forceinline__ float bf_hi_part(float x) { return __uint_as_float(cvtpk(x, 0.f) << 16); }
; template <int TYPE>
; __device__ __forceinline__ void conv_store(const ConvRegs& c, const Args& a, int l, int h, size_t rowq, int lane) {
; #pragma unroll
;     for (int i = 0; i < 4; ++i) { const size_t grow = rowq + i * 8 + (lane >> 3);
;         float* ko = a.out + (TYPE == 0 ? O_FKP : O_SKP) + ((size_t)l * MP + grow) * W + h * HD + (lane & 7) * 8;
;         float* vo = a.out + (TYPE == 0 ? O_FVP : O_SVP) + ((size_t)l * MP + grow) * W + h * HD + (lane & 7) * 8;
;         const u32x4 kw = c.k[i], vw = c.v[i];
;         __builtin_nontemporal_store((f32x4){bflo(kw.x), bfhi(kw.x), bflo(kw.y), bfhi(kw.y)}, (f32x4*)ko); __builtin_nontemporal_store((f32x4){bflo(kw.z), bfhi(kw.z), bflo(kw.w), bfhi(kw.w)}, (f32x4*)(ko + 4));
;         __builtin_nontemporal_store((f32x4){bflo(vw.x), bfhi(vw.x), bflo(vw.y), bfhi(vw.y)}, (f32x4*)vo); __builtin_nontemporal_store((f32x4){bflo(vw.z), bfhi(vw.z), bflo(vw.w), bfhi(vw.w)}, (f32x4*)(vo + 4)); }
; }
; __device__ __forceinline__ void prompt_unit_fox(const Args& a, int l, int b, int h, int qb, LAS unsigned char* lds) {
;     ...
;     { const int idx = tid * 4; if (idx < q0 + 256) { const f32x4 c = *(const f32x4*)((const float*)(a.ws + WS_CKP) + (size_t)(b * 8 + h) * T + idx); *(LAS f32x4*)(lds + F_CK + idx * 4) = c;
; #pragma unroll
;         for (int e = 0; e < 4; ++e) { const float h1 = bf_hi_part(c[e]), r1 = c[e] - h1, h2 = bf_hi_part(r1), r2 = r1 - h2; ((LAS u32x2*)(lds + F_AUG))[idx + e] = (u32x2){cvtpk(h1, h2), cvtpk(r2, -1.0f)}; } } }
	s_cmp_lg_u32 s83, 0
	s_cbranch_scc0 .Lck_skip_l0
	s_waitcnt vmcnt(20)
	ds_write_b128 v85, v[92:95]
	v_cvt_pk_bf16_f32 v85, v92, 0
	v_cvt_pk_bf16_f32 v87, v93, 0
	v_cvt_pk_bf16_f32 v88, v94, 0
	v_cvt_pk_bf16_f32 v91, v95, 0
	v_lshlrev_b32_e32 v85, 16, v85
	v_lshlrev_b32_e32 v87, 16, v87
	v_lshlrev_b32_e32 v88, 16, v88
	v_lshlrev_b32_e32 v91, 16, v91
	v_sub_f32_e32 v92, v92, v85
	v_sub_f32_e32 v93, v93, v87
	v_sub_f32_e32 v96, v94, v88
	v_sub_f32_e32 v95, v95, v91
	v_cvt_pk_bf16_f32 v94, v92, 0
	v_cvt_pk_bf16_f32 v97, v93, 0
	v_cvt_pk_bf16_f32 v98, v96, 0
	v_cvt_pk_bf16_f32 v99, v95, 0
	v_lshlrev_b32_e32 v94, 16, v94
	v_lshlrev_b32_e32 v97, 16, v97
	v_lshlrev_b32_e32 v98, 16, v98
	v_lshlrev_b32_e32 v99, 16, v99
	v_sub_f32_e32 v100, v92, v94
	v_cvt_pk_bf16_f32 v92, v85, v94
	v_sub_f32_e32 v85, v93, v97
	v_cvt_pk_bf16_f32 v94, v87, v97
	v_sub_f32_e32 v87, v96, v98
	v_cvt_pk_bf16_f32 v96, v88, v98
	v_sub_f32_e32 v88, v95, v99
	v_cvt_pk_bf16_f32 v93, v100, -1.0
	v_cvt_pk_bf16_f32 v95, v85, -1.0
	v_cvt_pk_bf16_f32 v98, v91, v99
	v_cvt_pk_bf16_f32 v97, v87, -1.0
	v_cvt_pk_bf16_f32 v99, v88, -1.0
	ds_write_b128 v86, v[92:95]
	ds_write_b128 v86, v[96:99] offset:16
.Lck_skip_l0:
	s_waitcnt vmcnt(18)
	v_lshlrev_b32_e32 v54, 16, v22
	v_and_b32_e32 v55, 0xffff0000, v22
	v_lshlrev_b32_e32 v56, 16, v23
	v_and_b32_e32 v57, 0xffff0000, v23
	v_lshlrev_b32_e32 v22, 16, v24
	v_and_b32_e32 v23, 0xffff0000, v24
	v_lshlrev_b32_e32 v24, 16, v25
	v_and_b32_e32 v25, 0xffff0000, v25
	global_store_dwordx4 v[2:3], v[22:25], off offset:128
	global_store_dwordx4 v[2:3], v[54:57], off
	v_lshl_add_u64 v[2:3], s[4:5], 0, v[58:59]
	s_waitcnt vmcnt(18)
	v_lshlrev_b32_e32 v22, 16, v26
	v_and_b32_e32 v23, 0xffff0000, v26
	v_lshlrev_b32_e32 v24, 16, v27
	v_and_b32_e32 v25, 0xffff0000, v27
	global_store_dwordx4 v[64:65], v[22:25], off
	v_lshl_add_u64 v[2:3], v[2:3], 0, s[0:1]
	v_lshl_add_u64 v[2:3], v[2:3], 0, v[4:5]
	v_lshlrev_b32_e32 v22, 16, v28
	v_and_b32_e32 v23, 0xffff0000, v28
	v_lshlrev_b32_e32 v24, 16, v29
	v_and_b32_e32 v25, 0xffff0000, v29
	global_store_dwordx4 v[64:65], v[22:25], off offset:128
	v_mov_b32_e32 v54, v5
	v_mov_b32_e32 v55, v5
	v_lshl_add_u64 v[22:23], s[8:9], 0, v[58:59]
	v_lshl_add_u64 v[22:23], v[22:23], 0, s[0:1]
	v_lshl_add_u64 v[26:27], v[22:23], 0, v[4:5]
	s_waitcnt vmcnt(18)
	v_lshlrev_b32_e32 v22, 16, v30
	v_and_b32_e32 v23, 0xffff0000, v30
	v_lshlrev_b32_e32 v24, 16, v31
	v_and_b32_e32 v25, 0xffff0000, v31
	global_store_dwordx4 v[2:3], v[22:25], off
	v_mov_b32_e32 v56, v5
	v_mov_b32_e32 v57, v5
	v_lshlrev_b32_e32 v22, 16, v32
	v_and_b32_e32 v23, 0xffff0000, v32
	v_lshlrev_b32_e32 v24, 16, v33
	v_and_b32_e32 v25, 0xffff0000, v33
	global_store_dwordx4 v[2:3], v[22:25], off offset:128
	v_lshl_add_u64 v[2:3], s[4:5], 0, v[60:61]
	v_lshl_add_u64 v[2:3], v[2:3], 0, s[0:1]
	s_waitcnt vmcnt(18)
	v_lshlrev_b32_e32 v22, 16, v34
	v_and_b32_e32 v23, 0xffff0000, v34
	v_lshlrev_b32_e32 v24, 16, v35
	v_and_b32_e32 v25, 0xffff0000, v35
	global_store_dwordx4 v[26:27], v[22:25], off
	v_lshl_add_u64 v[2:3], v[2:3], 0, v[4:5]
	v_mov_b32_e32 v58, v5
	v_lshlrev_b32_e32 v22, 16, v36
	v_and_b32_e32 v23, 0xffff0000, v36
	v_lshlrev_b32_e32 v24, 16, v37
	v_and_b32_e32 v25, 0xffff0000, v37
	global_store_dwordx4 v[26:27], v[22:25], off offset:128
	v_mov_b32_e32 v59, v5
	v_mov_b32_e32 v64, v5
	v_lshl_add_u64 v[22:23], s[8:9], 0, v[60:61]
	v_lshl_add_u64 v[22:23], v[22:23], 0, s[0:1]
	v_lshl_add_u64 v[26:27], v[22:23], 0, v[4:5]
	s_waitcnt vmcnt(18)
	v_lshlrev_b32_e32 v22, 16, v38
	v_and_b32_e32 v23, 0xffff0000, v38
	v_lshlrev_b32_e32 v24, 16, v39
	v_and_b32_e32 v25, 0xffff0000, v39
	global_store_dwordx4 v[2:3], v[22:25], off
	v_mov_b32_e32 v60, v5
	v_mov_b32_e32 v61, v5
	v_lshlrev_b32_e32 v22, 16, v40
	v_and_b32_e32 v23, 0xffff0000, v40
	v_lshlrev_b32_e32 v24, 16, v41
	v_and_b32_e32 v25, 0xffff0000, v41
	global_store_dwordx4 v[2:3], v[22:25], off offset:128
	v_lshl_add_u64 v[2:3], s[4:5], 0, v[62:63]
	v_lshl_add_u64 v[2:3], v[2:3], 0, s[0:1]
	s_waitcnt vmcnt(18)
	v_lshlrev_b32_e32 v22, 16, v42
	v_and_b32_e32 v23, 0xffff0000, v42
	v_lshlrev_b32_e32 v24, 16, v43
	v_and_b32_e32 v25, 0xffff0000, v43
	global_store_dwordx4 v[26:27], v[22:25], off
	v_lshl_add_u64 v[2:3], v[2:3], 0, v[4:5]
	v_mov_b32_e32 v65, v5
	v_lshlrev_b32_e32 v22, 16, v44
	v_and_b32_e32 v23, 0xffff0000, v44
	v_lshlrev_b32_e32 v24, 16, v45
	v_and_b32_e32 v25, 0xffff0000, v45
	global_store_dwordx4 v[26:27], v[22:25], off offset:128
	v_mov_b32_e32 v157, v5
	v_mov_b32_e32 v158, v5
	v_lshl_add_u64 v[22:23], s[8:9], 0, v[62:63]
	v_lshl_add_u64 v[22:23], v[22:23], 0, s[0:1]
	v_lshl_add_u64 v[26:27], v[22:23], 0, v[4:5]
	s_waitcnt vmcnt(14)
; __device__ __forceinline__ float bflo(unsigned w) { return __uint_as_float(w << 16); }
; __device__ __forceinline__ float bfhi(unsigned w) { return __uint_as_float(w & 0xffff0000u); }
; #define ATT_WAIT_BAR() asm volatile("s_waitcnt vmcnt(0) lgkmcnt(0)\n\ts_barrier" ::: "memory")
; template <int TYPE>
; __device__ __forceinline__ void conv_store(const ConvRegs& c, const Args& a, int l, int h, size_t rowq, int lane) {
; #pragma unroll
;     for (int i = 0; i < 4; ++i) { const size_t grow = rowq + i * 8 + (lane >> 3);
;         float* ko = a.out + (TYPE == 0 ? O_FKP : O_SKP) + ((size_t)l * MP + grow) * W + h * HD + (lane & 7) * 8;
;         float* vo = a.out + (TYPE == 0 ? O_FVP : O_SVP) + ((size_t)l * MP + grow) * W + h * HD + (lane & 7) * 8;
;         const u32x4 kw = c.k[i], vw = c.v[i];
;         __builtin_nontemporal_store((f32x4){bflo(kw.x), bfhi(kw.x), bflo(kw.y), bfhi(kw.y)}, (f32x4*)ko); __builtin_nontemporal_store((f32x4){bflo(kw.z), bfhi(kw.z), bflo(kw.w), bfhi(kw.w)}, (f32x4*)(ko + 4));
;         __builtin_nontemporal_store((f32x4){bflo(vw.x), bfhi(vw.x), bflo(vw.y), bfhi(vw.y)}, (f32x4*)vo); __builtin_nontemporal_store((f32x4){bflo(vw.z), bfhi(vw.z), bflo(vw.w), bfhi(vw.w)}, (f32x4*)(vo + 4)); }
; }
; __device__ __forceinline__ void prompt_unit_fox(const Args& a, int l, int b, int h, int qb, LAS unsigned char* lds) {
;     ...
;     FoxState st; st.m = 0.f; st.l = 0.f; st.mq = (bf16x8){}; st.o[0] = (f32x16){}; st.o[1] = (f32x16){};
;     PairP pp; bool pending = false;
; #pragma unroll
;     for (int i = 0; i < 8; ++i) pp.w[i] = (u32x4){0u, 0u, 0u, 0u};
;     { ConvRegs cv; conv_load(cv, a, rowb + q0 + wid * 32, col, lane); conv_store<0>(cv, a, l, h, rowb + q0 + wid * 32, lane); }
;     int slot = 0, pslot = 0;
;     ...
;         ATT_WAIT_BAR();
	v_lshlrev_b32_e32 v22, 16, v46
	v_and_b32_e32 v23, 0xffff0000, v46
	v_lshlrev_b32_e32 v24, 16, v47
	v_and_b32_e32 v25, 0xffff0000, v47
	global_store_dwordx4 v[2:3], v[22:25], off
	s_add_i32 s1, 0, 0x18000
	v_add_u32_e32 v184, s1, v172
	v_lshlrev_b32_e32 v22, 16, v48
	v_and_b32_e32 v23, 0xffff0000, v48
	v_lshlrev_b32_e32 v24, 16, v49
	v_and_b32_e32 v25, 0xffff0000, v49
	global_store_dwordx4 v[2:3], v[22:25], off offset:128
	v_or_b32_e32 v2, 32, v66
	v_cmp_gt_u32_e64 s[10:11], v2, v67
	v_or_b32_e32 v2, 33, v66
	v_cmp_gt_u32_e64 s[14:15], v2, v67
	v_or_b32_e32 v2, 2, v66
	v_cmp_gt_u32_e64 s[16:17], v2, v67
	v_or_b32_e32 v2, 34, v66
	v_cmp_gt_u32_e64 s[18:19], v2, v67
	v_or_b32_e32 v2, 3, v66
	v_cmp_gt_u32_e64 s[20:21], v2, v67
	v_or_b32_e32 v2, 35, v66
	v_cmp_gt_u32_e64 s[22:23], v2, v67
	v_or_b32_e32 v2, 8, v66
	v_cmp_gt_u32_e64 s[24:25], v2, v67
	v_or_b32_e32 v2, 40, v66
	v_cmp_gt_u32_e64 s[26:27], v2, v67
	v_or_b32_e32 v2, 9, v66
	v_cmp_gt_u32_e64 s[28:29], v2, v67
	v_or_b32_e32 v2, 41, v66
	v_cmp_gt_u32_e64 s[30:31], v2, v67
	v_or_b32_e32 v2, 10, v66
	v_cmp_gt_u32_e64 s[34:35], v2, v67
	v_or_b32_e32 v2, 42, v66
	v_cmp_gt_u32_e64 s[36:37], v2, v67
	v_or_b32_e32 v2, 11, v66
	v_cmp_gt_u32_e64 s[38:39], v2, v67
	v_or_b32_e32 v2, 43, v66
	v_cmp_gt_u32_e64 s[40:41], v2, v67
	v_or_b32_e32 v2, 16, v66
	v_cmp_gt_u32_e64 s[42:43], v2, v67
	v_or_b32_e32 v2, 48, v66
	v_cmp_gt_u32_e64 s[44:45], v2, v67
	v_or_b32_e32 v2, 17, v66
	v_cmp_gt_u32_e64 s[46:47], v2, v67
	v_or_b32_e32 v2, 49, v66
	v_cmp_gt_u32_e64 s[48:49], v2, v67
	v_or_b32_e32 v2, 18, v66
	v_cmp_gt_u32_e64 s[50:51], v2, v67
	v_or_b32_e32 v2, 50, v66
	v_cmp_gt_u32_e64 s[52:53], v2, v67
	v_or_b32_e32 v2, 19, v66
	v_cmp_gt_u32_e64 s[54:55], v2, v67
	v_or_b32_e32 v2, 51, v66
	v_cmp_gt_u32_e64 s[56:57], v2, v67
	v_or_b32_e32 v2, 24, v66
	v_cmp_gt_u32_e64 s[58:59], v2, v67
	v_or_b32_e32 v2, 56, v66
	v_cmp_gt_u32_e64 s[60:61], v2, v67
	v_or_b32_e32 v2, 25, v66
	v_cmp_gt_u32_e64 s[62:63], v2, v67
	v_or_b32_e32 v2, 57, v66
	v_cmp_gt_u32_e64 s[64:65], v2, v67
	v_or_b32_e32 v2, 26, v66
	v_cmp_gt_u32_e64 s[66:67], v2, v67
	v_or_b32_e32 v2, 58, v66
	v_cmp_gt_u32_e64 s[68:69], v2, v67
	v_or_b32_e32 v2, 27, v66
	v_cmp_gt_u32_e64 s[70:71], v2, v67
	v_or_b32_e32 v2, 59, v66
	s_waitcnt vmcnt(14)
	v_lshlrev_b32_e32 v22, 16, v50
	v_and_b32_e32 v23, 0xffff0000, v50
	v_lshlrev_b32_e32 v24, 16, v51
	v_and_b32_e32 v25, 0xffff0000, v51
	s_add_i32 s1, 0, 0x1a800
	v_cmp_gt_u32_e64 s[8:9], v66, v67
	v_cmp_gt_u32_e64 s[72:73], v2, v67
	v_mov_b32_e32 v66, v5
	v_mov_b32_e32 v67, v5
	global_store_dwordx4 v[26:27], v[22:25], off
	s_bitcmp1_b32 s3, 7
	v_mov_b32_e32 v62, v5
	v_lshlrev_b32_e32 v22, 16, v52
	v_and_b32_e32 v23, 0xffff0000, v52
	v_lshlrev_b32_e32 v24, 16, v53
	v_and_b32_e32 v25, 0xffff0000, v53
	v_mov_b32_e32 v52, v5
	v_mov_b32_e32 v53, v5
	v_mov_b32_e32 v63, v5
	v_mov_b64_e32 v[82:83], v[66:67]
	v_lshl_add_u32 v186, v175, 3, s1
	s_cselect_b64 s[94:95], -1, 0
	s_mov_b32 s1, 0
	v_mov_b32_e32 v159, v5
	v_mov_b32_e32 v192, 0
	v_mov_b32_e32 v124, 0
	v_mov_b32_e32 v125, 0
	v_mov_b32_e32 v126, 0
	v_mov_b32_e32 v127, 0
	v_mov_b32_e32 v128, 0
	v_mov_b32_e32 v129, 0
	v_mov_b32_e32 v130, 0
	v_mov_b32_e32 v131, 0
	v_mov_b32_e32 v132, 0
	v_mov_b32_e32 v133, 0
	v_mov_b32_e32 v134, 0
	v_mov_b32_e32 v135, 0
	v_mov_b32_e32 v136, 0
	v_mov_b32_e32 v137, 0
	v_mov_b32_e32 v138, 0
	v_mov_b32_e32 v139, 0
	v_mov_b32_e32 v140, 0
	v_mov_b32_e32 v141, 0
	v_mov_b32_e32 v142, 0
	v_mov_b32_e32 v143, 0
	v_mov_b32_e32 v144, 0
	v_mov_b32_e32 v145, 0
	v_mov_b32_e32 v146, 0
	v_mov_b32_e32 v147, 0
	v_mov_b32_e32 v148, 0
	v_mov_b32_e32 v149, 0
	v_mov_b32_e32 v150, 0
	v_mov_b32_e32 v151, 0
	v_mov_b32_e32 v152, 0
	v_mov_b32_e32 v153, 0
	v_mov_b32_e32 v154, 0
	v_mov_b32_e32 v155, 0
	v_cndmask_b32_e64 v2, 0, v187, s[6:7]
	s_mov_b32 s75, 0
	v_mov_b64_e32 v[80:81], v[64:65]
	v_mov_b64_e32 v[78:79], v[62:63]
	v_mov_b64_e32 v[76:77], v[60:61]
	v_mov_b64_e32 v[74:75], v[58:59]
	v_mov_b64_e32 v[72:73], v[56:57]
	v_mov_b64_e32 v[70:71], v[54:55]
	v_mov_b64_e32 v[68:69], v[52:53]
	v_mov_b32_e32 v193, 0
	s_mov_b64 s[4:5], 0
	global_store_dwordx4 v[26:27], v[22:25], off offset:128
	s_waitcnt vmcnt(16) lgkmcnt(0)
	s_barrier
	v_mov_b64_e32 v[20:21], 0
	v_mov_b64_e32 v[22:23], 0
	v_mov_b64_e32 v[24:25], 0
	v_mov_b64_e32 v[26:27], 0
	v_mov_b64_e32 v[28:29], 0
	v_mov_b64_e32 v[30:31], 0
	v_mov_b64_e32 v[32:33], 0
	v_mov_b64_e32 v[34:35], 0
	v_mov_b64_e32 v[36:37], 0
	v_mov_b64_e32 v[38:39], 0
	v_mov_b64_e32 v[40:41], 0
	v_mov_b64_e32 v[42:43], 0
	v_mov_b64_e32 v[44:45], 0
	v_mov_b64_e32 v[46:47], 0
	v_mov_b64_e32 v[48:49], 0
	v_mov_b64_e32 v[50:51], 0
	s_branch .Lfox_top_l0

; #define LAS __attribute__((address_space(3)))
; __device__ __forceinline__ void make_tri(f16x8& T00, f16x8& T01, int r32, int hi) {
; #pragma unroll
;     for (int j = 0; j < 8; ++j) { const int kin = 8 * (j >> 2) + 4 * hi + (j & 3);
;         T00[j] = (kin >= r32) ? (_Float16)-1.0f : (_Float16)0.0f; T01[j] = (16 + kin >= r32) ? (_Float16)-1.0f : (_Float16)0.0f; }
; }
; __device__ __forceinline__ void prompt_unit_sb(const Args& a, int l, int b, int h, int qb, LAS unsigned char* lds) {
;     int tid_ = threadIdx.x; asm volatile("" : "+v"(tid_));
;     const int tid = tid_, lane = tid & 63, r32 = lane & 31, hi = lane >> 5, wid = __builtin_amdgcn_readfirstlane(tid >> 6);
;     f16x8 T00, T01; make_tri(T00, T01, r32, hi);
;     const int q0 = qb * 256, jb = q0 / 64, jd = jb + (wid >> 1);
;     const int col = W + h * HD;
;     const size_t rowb = (size_t)b * T;
;     const bf16* Kh = (const bf16*)(a.ws + WS_K) + rowb * D + col; const bf16* Vh = (const bf16*)(a.ws + WS_V) + rowb * D + col;
;     const unsigned lds0 = (unsigned)(uintptr_t)lds;
;     const bf16* ksrc = Kh + (size_t)lane * D + wid * 8;
;     const bf16* vsrc = Vh + (size_t)(16 * (wid & 3) + (lane >> 2)) * D + (wid >> 2) * 32 + (lane & 3) * 8;
;     ...
;     ATT_DMA(jb + 3); ATT_DMA(jb + 2); ATT_DMA(jb + 1); ATT_DMA(jb);
;     if (jb >= 4) { ATT_DMA(jb - 1); ATT_DMA(jb - 2); ATT_DMA(jb - 3); }
;     bf16x8 qr[4];
;     { const bf16* Qw = (const bf16*)(a.ws + WS_Q) + (rowb + q0 + wid * 32 + r32) * D + col;
; #pragma unroll
;       for (int d0 = 0; d0 < 4; ++d0) qr[d0] = *(const bf16x8*)(Qw + d0 * 16 + hi * 8); }
;     const lds_cptr vp0 = (lds_cptr)lds + B_V + ((lane >> 4) & 1) * 32 + (lane & 3) * 8 + (4 * hi + ((lane & 15) >> 2)) * 64;
;     const int qlim = 32 * (wid & 1) + r32;
;     LAS float* wsf = (LAS float*)(lds + B_WSF) + wid * 64;
;     LAS unsigned* flags = (LAS unsigned*)(lds + B_FLAG);
;     FoxState st; st.m = 0.f; st.l = 0.f; st.mq = (bf16x8){}; st.o[0] = (f32x16){}; st.o[1] = (f32x16){};
;     float R = 0.f; bool done = false;
;     { ConvRegs cv; conv_load(cv, a, rowb + q0 + wid * 32, col, lane); conv_store<1>(cv, a, l, h, rowb + q0 + wid * 32, lane); }
.LBB0_928:
	v_lshrrev_b32_e32 v46, 5, v53
	v_and_b32_e32 v169, 31, v19
	v_lshlrev_b32_e32 v47, 2, v46
	v_cmp_lt_u32_e32 vcc, v47, v169
	v_or_b32_e32 v48, 16, v47
	v_or_b32_e32 v50, 1, v47
	v_cndmask_b32_e64 v3, v179, 0, vcc
	v_cmp_lt_u32_e32 vcc, v48, v169
	v_or_b32_e32 v49, 2, v47
	s_lshl_b32 s3, s7, 8
	v_cndmask_b32_e64 v24, v179, 0, vcc
	v_cmp_lt_u32_e32 vcc, v50, v169
	v_or_b32_e32 v52, 17, v47
	s_ashr_i32 s2, s8, 7
	v_cndmask_b32_e64 v14, v179, 0, vcc
	v_cmp_lt_u32_e32 vcc, v49, v169
	s_ashr_i32 s7, s3, 31
	v_or_b32_e32 v51, 18, v47
	v_cndmask_b32_e64 v15, v179, 0, vcc
	v_cmp_lt_u32_e32 vcc, v52, v169
	s_add_u32 s3, s3, s9
	v_or_b32_e32 v55, 3, v47
	v_cndmask_b32_e64 v25, v179, 0, vcc
	v_cmp_lt_u32_e32 vcc, v51, v169
	s_addc_u32 s7, s7, 0
	s_lshl_b32 s8, s84, 5
	v_cndmask_b32_e64 v26, v179, 0, vcc
	v_or_b32_e32 v54, 8, v47
	v_cmp_lt_u32_e32 vcc, v55, v169
	s_ashr_i32 s9, s8, 31
	v_or_b32_e32 v57, 19, v47
	v_cndmask_b32_e64 v16, v179, 0, vcc
	v_cmp_lt_u32_e32 vcc, v54, v169
	s_add_u32 s82, s3, s8
	v_or_b32_e32 v56, 24, v47
	v_cndmask_b32_e64 v17, v179, 0, vcc
	v_cmp_lt_u32_e32 vcc, v57, v169
	s_addc_u32 s83, s7, s9
	v_or_b32_e32 v58, 10, v47
	v_cndmask_b32_e64 v27, v179, 0, vcc
	v_cmp_lt_u32_e32 vcc, v56, v169
	v_or_b32_e32 v160, s82, v169
	v_mov_b32_e32 v161, s83
	v_readlane_b32 s10, v242, 28
	v_cndmask_b32_e64 v28, v179, 0, vcc
	v_or_b32_e32 v59, 9, v47
	v_cmp_lt_u32_e32 vcc, v58, v169
	v_lshlrev_b64 v[6:7], 11, v[160:161]
	v_readlane_b32 s11, v242, 29
	v_cndmask_b32_e64 v22, v179, 0, vcc
	v_cmp_lt_u32_e32 vcc, v59, v169
	v_or_b32_e32 v60, 26, v47
	v_lshl_add_u64 v[6:7], s[10:11], 0, v[6:7]
	s_lshl_b32 s78, s6, 1
	s_mov_b32 s79, s87
	v_lshrrev_b32_e32 v1, 3, v53
	v_cndmask_b32_e64 v23, v179, 0, vcc
	v_or_b32_e32 v61, 25, v47
	v_lshl_add_u64 v[6:7], v[6:7], 0, s[78:79]
	v_lshlrev_b32_e32 v4, 4, v46
	v_or_b32_e32 v160, s82, v1
	v_readlane_b32 s10, v242, 20
	v_cmp_lt_u32_e32 vcc, v60, v169
	v_lshl_add_u64 v[20:21], v[6:7], 0, v[4:5]
	v_lshlrev_b32_e32 v4, 3, v53
	v_lshlrev_b64 v[162:163], 11, v[160:161]
	v_readlane_b32 s11, v242, 21
	v_cndmask_b32_e64 v29, v179, 0, vcc
	v_cmp_lt_u32_e32 vcc, v61, v169
	v_or_b32_e32 v62, 11, v47
	v_readlane_b32 s12, v242, 22
	v_and_b32_e32 v168, 56, v4
	v_lshl_add_u64 v[6:7], s[10:11], 0, v[162:163]
	v_cndmask_b32_e64 v30, v179, 0, vcc
	v_readlane_b32 s13, v242, 23
	v_cmp_lt_u32_e32 vcc, v62, v169
	v_lshl_add_u64 v[6:7], v[6:7], 0, s[78:79]
	v_mov_b32_e32 v4, v168
	v_lshl_add_u64 v[10:11], s[12:13], 0, v[162:163]
	v_cndmask_b32_e64 v31, v179, 0, vcc
	v_lshl_add_u64 v[6:7], v[6:7], 0, v[4:5]
	v_lshl_add_u64 v[10:11], v[10:11], 0, s[78:79]
	v_pack_b32_f16 v118, v17, v23
	v_pack_b32_f16 v119, v22, v31
	v_or_b32_e32 v63, 27, v47
	v_or_b32_e32 v22, 0x4000, v162
	v_mov_b32_e32 v23, v163
	global_load_dwordx2 v[8:9], v[6:7], off offset:1088
	global_load_dwordx2 v[6:7], v[6:7], off offset:1024
	v_lshl_add_u64 v[10:11], v[10:11], 0, v[4:5]
	v_pack_b32_f16 v117, v15, v16
	v_pack_b32_f16 v116, v3, v14
	v_lshl_add_u64 v[14:15], s[10:11], 0, v[22:23]
	v_cmp_lt_u32_e32 vcc, v63, v169
	global_load_dwordx2 v[12:13], v[10:11], off offset:1088
	global_load_dwordx2 v[10:11], v[10:11], off offset:1024
	v_lshl_add_u64 v[14:15], v[14:15], 0, s[78:79]
	v_cndmask_b32_e64 v3, v179, 0, vcc
	v_lshl_add_u64 v[14:15], v[14:15], 0, v[4:5]
	v_pack_b32_f16 v123, v29, v3
	v_lshlrev_b32_e32 v3, 1, v19
	global_load_dwordx2 v[16:17], v[14:15], off offset:1088
	global_load_dwordx2 v[14:15], v[14:15], off offset:1024
	v_pack_b32_f16 v120, v24, v25
	v_and_b32_e32 v3, 32, v3
	s_add_i32 s3, 0, 0x10000
	v_lshlrev_b32_e32 v24, 4, v19
	global_load_dwordx4 v[124:127], v[20:21], off offset:1024
	global_load_dwordx4 v[128:131], v[20:21], off offset:1056
	global_load_dwordx4 v[132:135], v[20:21], off offset:1088
	global_load_dwordx4 v[136:139], v[20:21], off offset:1120
	v_lshl_add_u64 v[20:21], s[12:13], 0, v[22:23]
	v_add3_u32 v2, s3, v3, v2
	v_lshlrev_b32_e32 v3, 8, v46
	v_and_b32_e32 v24, 0xc0, v24
	v_lshl_add_u64 v[20:21], v[20:21], 0, s[78:79]
	v_add3_u32 v170, v2, v3, v24
	v_or_b32_e32 v2, 0x8000, v162
	v_mov_b32_e32 v3, v163
	v_lshl_add_u64 v[20:21], v[20:21], 0, v[4:5]
	v_lshl_add_u64 v[24:25], s[10:11], 0, v[2:3]
	global_load_dwordx2 v[22:23], v[20:21], off offset:1088
	global_load_dwordx2 v[20:21], v[20:21], off offset:1024
	v_lshl_add_u64 v[24:25], v[24:25], 0, s[78:79]
	v_lshl_add_u64 v[24:25], v[24:25], 0, v[4:5]
	v_lshl_add_u64 v[2:3], s[12:13], 0, v[2:3]
	v_pack_b32_f16 v121, v26, v27
	global_load_dwordx2 v[26:27], v[24:25], off offset:1088
	global_load_dwordx2 v[24:25], v[24:25], off offset:1024
	v_lshl_add_u64 v[2:3], v[2:3], 0, s[78:79]
	v_lshl_add_u64 v[2:3], v[2:3], 0, v[4:5]
	v_pack_b32_f16 v122, v28, v30
	global_load_dwordx2 v[30:31], v[2:3], off offset:1088
	global_load_dwordx2 v[28:29], v[2:3], off offset:1024
	v_or_b32_e32 v2, 0xc000, v162
	v_mov_b32_e32 v3, v163
	v_lshl_add_u64 v[32:33], s[10:11], 0, v[2:3]
	v_lshl_add_u64 v[32:33], v[32:33], 0, s[78:79]
	v_lshl_add_u64 v[2:3], s[12:13], 0, v[2:3]
	v_lshl_add_u64 v[32:33], v[32:33], 0, v[4:5]
	v_lshl_add_u64 v[2:3], v[2:3], 0, s[78:79]
	v_lshl_add_u64 v[2:3], v[2:3], 0, v[4:5]
	global_load_dwordx2 v[34:35], v[32:33], off offset:1088
	global_load_dwordx2 v[32:33], v[32:33], off offset:1024
	s_nop 0
	global_load_dwordx2 v[38:39], v[2:3], off offset:1088
	global_load_dwordx2 v[36:37], v[2:3], off offset:1024
	s_add_u32 s3, s82, 0x10000
	s_addc_u32 s7, s83, 0
	v_and_or_b32 v64, s8, 32, v169
	v_or_b32_e32 v2, s3, v1
	v_mov_b32_e32 v3, s7
	v_readlane_b32 s8, v242, 16
	v_lshlrev_b64 v[2:3], 11, v[2:3]
	v_readlane_b32 s9, v242, 17
	s_lshl_b32 s92, s6, 2
	v_readlane_b32 s6, v242, 24
	v_lshl_add_u64 v[40:41], s[8:9], 0, v[2:3]
	s_mov_b32 s93, s87
	v_readlane_b32 s7, v242, 25
	v_lshl_add_u64 v[40:41], v[40:41], 0, s[92:93]
	v_lshlrev_b32_e32 v4, 1, v168
	v_lshl_add_u64 v[2:3], s[6:7], 0, v[2:3]
	v_lshl_add_u64 v[44:45], v[40:41], 0, v[4:5]
	v_lshl_add_u64 v[2:3], v[2:3], 0, s[92:93]
	v_lshl_add_u64 v[2:3], v[2:3], 0, v[4:5]
	s_movk_i32 s3, 0x4000
	s_mov_b64 s[6:7], 0x4000
	v_lshlrev_b32_e32 v171, 10, v46
	v_cmp_lt_u32_e64 s[10:11], v50, v64
	v_cmp_lt_u32_e64 s[14:15], v49, v64
	v_cmp_lt_u32_e64 s[18:19], v55, v64
	v_cmp_lt_u32_e64 s[22:23], v54, v64
	v_cmp_lt_u32_e64 s[40:41], v48, v64
	v_cmp_lt_u32_e64 s[48:49], v51, v64
	v_or_b32_e32 v54, 58, v47
	v_or_b32_e32 v55, 59, v47
	v_mov_b32_e32 v4, v5
	s_mov_b32 s79, 0
	v_cmp_lt_u32_e64 s[26:27], v59, v64

; #define LAS __attribute__((address_space(3)))
; __device__ __forceinline__ float bflo(unsigned w) { return __uint_as_float(w << 16); }
; __device__ __forceinline__ float bfhi(unsigned w) { return __uint_as_float(w & 0xffff0000u); }
; template <int TYPE>
; __device__ __forceinline__ void conv_store(const ConvRegs& c, const Args& a, int l, int h, size_t rowq, int lane) {
; #pragma unroll
;     for (int i = 0; i < 4; ++i) { const size_t grow = rowq + i * 8 + (lane >> 3);
;         float* ko = a.out + (TYPE == 0 ? O_FKP : O_SKP) + ((size_t)l * MP + grow) * W + h * HD + (lane & 7) * 8;
;         float* vo = a.out + (TYPE == 0 ? O_FVP : O_SVP) + ((size_t)l * MP + grow) * W + h * HD + (lane & 7) * 8;
;         const u32x4 kw = c.k[i], vw = c.v[i];
;         __builtin_nontemporal_store((f32x4){bflo(kw.x), bfhi(kw.x), bflo(kw.y), bfhi(kw.y)}, (f32x4*)ko); __builtin_nontemporal_store((f32x4){bflo(kw.z), bfhi(kw.z), bflo(kw.w), bfhi(kw.w)}, (f32x4*)(ko + 4));
;         __builtin_nontemporal_store((f32x4){bflo(vw.x), bfhi(vw.x), bflo(vw.y), bfhi(vw.y)}, (f32x4*)vo); __builtin_nontemporal_store((f32x4){bflo(vw.z), bfhi(vw.z), bflo(vw.w), bfhi(vw.w)}, (f32x4*)(vo + 4)); }
; }
; __device__ __forceinline__ void prompt_unit_sb(const Args& a, int l, int b, int h, int qb, LAS unsigned char* lds) {
;     ...
;     LAS unsigned* flags = (LAS unsigned*)(lds + B_FLAG);
;     FoxState st; st.m = 0.f; st.l = 0.f; st.mq = (bf16x8){}; st.o[0] = (f32x16){}; st.o[1] = (f32x16){};
;     float R = 0.f; bool done = false;
;     { ConvRegs cv; conv_load(cv, a, rowb + q0 + wid * 32, col, lane); conv_store<1>(cv, a, l, h, rowb + q0 + wid * 32, lane); }
;     for (int it = 0; ; ++it) {
	s_waitcnt vmcnt(18)
	v_lshlrev_b32_e32 v40, 16, v6
	v_and_b32_e32 v41, 0xffff0000, v6
	v_lshlrev_b32_e32 v42, 16, v7
	v_and_b32_e32 v43, 0xffff0000, v7
	v_lshlrev_b32_e32 v6, 16, v8
	v_and_b32_e32 v7, 0xffff0000, v8
	v_lshlrev_b32_e32 v8, 16, v9
	v_and_b32_e32 v9, 0xffff0000, v9
	global_store_dwordx4 v[44:45], v[6:9], off offset:128
	global_store_dwordx4 v[44:45], v[40:43], off
	v_cmp_lt_u32_e64 s[30:31], v58, v64
	s_waitcnt vmcnt(18)
	v_lshlrev_b32_e32 v6, 16, v10
	v_and_b32_e32 v7, 0xffff0000, v10
	v_lshlrev_b32_e32 v8, 16, v11
	v_and_b32_e32 v9, 0xffff0000, v11
	global_store_dwordx4 v[2:3], v[6:9], off
	v_lshl_add_u64 v[10:11], v[44:45], 0, s[6:7]
	v_cmp_lt_u32_e64 s[36:37], v62, v64
	v_lshlrev_b32_e32 v6, 16, v12
	v_and_b32_e32 v7, 0xffff0000, v12
	v_lshlrev_b32_e32 v8, 16, v13
	v_and_b32_e32 v9, 0xffff0000, v13
	global_store_dwordx4 v[2:3], v[6:9], off offset:128
	v_lshl_add_u64 v[12:13], v[2:3], 0, s[6:7]
	s_mov_b64 s[6:7], 0x8000
	s_waitcnt vmcnt(18)
	v_lshlrev_b32_e32 v6, 16, v14
	v_and_b32_e32 v7, 0xffff0000, v14
	v_add_co_u32_e32 v14, vcc, s3, v44
	v_lshlrev_b32_e32 v8, 16, v15
	v_and_b32_e32 v9, 0xffff0000, v15
	v_addc_co_u32_e32 v15, vcc, 0, v45, vcc
	global_store_dwordx4 v[14:15], v[6:9], off
	v_cmp_lt_u32_e64 s[44:45], v52, v64
	v_cmp_lt_u32_e64 s[52:53], v57, v64
	v_lshlrev_b32_e32 v6, 16, v16
	v_and_b32_e32 v7, 0xffff0000, v16
	v_lshlrev_b32_e32 v8, 16, v17
	v_and_b32_e32 v9, 0xffff0000, v17
	global_store_dwordx4 v[10:11], v[6:9], off offset:128
	v_add_co_u32_e32 v10, vcc, s3, v2
	s_nop 0
	s_waitcnt vmcnt(14)
	v_lshlrev_b32_e32 v6, 16, v20
	v_and_b32_e32 v7, 0xffff0000, v20
	v_lshlrev_b32_e32 v8, 16, v21
	v_and_b32_e32 v9, 0xffff0000, v21
	v_addc_co_u32_e32 v11, vcc, 0, v3, vcc
	s_mov_b32 s3, 0x8000
	global_store_dwordx4 v[10:11], v[6:9], off
	v_add_co_u32_e32 v14, vcc, s3, v44
	s_nop 0
	v_lshlrev_b32_e32 v6, 16, v22
	v_and_b32_e32 v7, 0xffff0000, v22
	v_lshlrev_b32_e32 v8, 16, v23
	v_and_b32_e32 v9, 0xffff0000, v23
	global_store_dwordx4 v[12:13], v[6:9], off offset:128
	v_addc_co_u32_e32 v15, vcc, 0, v45, vcc
	s_nop 0
	s_waitcnt vmcnt(14)
	v_lshlrev_b32_e32 v6, 16, v24
	v_and_b32_e32 v7, 0xffff0000, v24
	v_lshlrev_b32_e32 v8, 16, v25
	v_and_b32_e32 v9, 0xffff0000, v25
	v_lshl_add_u64 v[10:11], v[44:45], 0, s[6:7]
	global_store_dwordx4 v[14:15], v[6:9], off
	v_lshl_add_u64 v[12:13], v[2:3], 0, s[6:7]
	s_mov_b64 s[6:7], 0xc000
	v_lshlrev_b32_e32 v6, 16, v26
	v_and_b32_e32 v7, 0xffff0000, v26
	v_lshlrev_b32_e32 v8, 16, v27
	v_and_b32_e32 v9, 0xffff0000, v27
	global_store_dwordx4 v[10:11], v[6:9], off offset:128
	v_add_co_u32_e32 v10, vcc, s3, v2
	s_nop 0
	s_waitcnt vmcnt(14)
	v_lshlrev_b32_e32 v6, 16, v28
	v_and_b32_e32 v7, 0xffff0000, v28
	v_lshlrev_b32_e32 v8, 16, v29
	v_and_b32_e32 v9, 0xffff0000, v29
	v_addc_co_u32_e32 v11, vcc, 0, v3, vcc
	s_mov_b32 s3, 0xc000
	global_store_dwordx4 v[10:11], v[6:9], off
	v_add_co_u32_e32 v14, vcc, s3, v44
	s_nop 0
	v_lshlrev_b32_e32 v6, 16, v30
	v_and_b32_e32 v7, 0xffff0000, v30
	v_lshlrev_b32_e32 v8, 16, v31
	v_and_b32_e32 v9, 0xffff0000, v31
	global_store_dwordx4 v[12:13], v[6:9], off offset:128
	v_addc_co_u32_e32 v15, vcc, 0, v45, vcc
	s_nop 0
	s_waitcnt vmcnt(14)
	v_lshlrev_b32_e32 v6, 16, v32
	v_and_b32_e32 v7, 0xffff0000, v32
	v_lshlrev_b32_e32 v8, 16, v33
	v_and_b32_e32 v9, 0xffff0000, v33
	v_lshl_add_u64 v[10:11], v[44:45], 0, s[6:7]
	v_lshl_add_u64 v[12:13], v[2:3], 0, s[6:7]
	global_store_dwordx4 v[14:15], v[6:9], off
	v_add_co_u32_e32 v2, vcc, s3, v2
	s_nop 0
	v_lshlrev_b32_e32 v6, 16, v34
	v_and_b32_e32 v7, 0xffff0000, v34
	v_lshlrev_b32_e32 v8, 16, v35
	v_and_b32_e32 v9, 0xffff0000, v35
	global_store_dwordx4 v[10:11], v[6:9], off offset:128
	v_addc_co_u32_e32 v3, vcc, 0, v3, vcc
	s_nop 0
	s_waitcnt vmcnt(14)
	v_lshlrev_b32_e32 v6, 16, v36
	v_and_b32_e32 v7, 0xffff0000, v36
	v_lshlrev_b32_e32 v8, 16, v37
	v_and_b32_e32 v9, 0xffff0000, v37
	global_store_dwordx4 v[2:3], v[6:9], off
	v_lshlrev_b32_e32 v2, 4, v169
	v_add3_u32 v172, 0, v171, v2
	v_or_b32_e32 v2, 32, v47
	v_cmp_lt_u32_e64 s[8:9], v2, v64
	v_or_b32_e32 v2, 33, v47
	v_cmp_lt_u32_e64 s[12:13], v2, v64
	v_or_b32_e32 v2, 34, v47
	v_cmp_lt_u32_e64 s[16:17], v2, v64
	v_or_b32_e32 v2, 35, v47
	v_cmp_lt_u32_e64 s[20:21], v2, v64
	v_or_b32_e32 v2, 40, v47
	v_cmp_lt_u32_e64 s[24:25], v2, v64
	v_or_b32_e32 v2, 41, v47
	v_cmp_lt_u32_e64 s[28:29], v2, v64
	v_or_b32_e32 v2, 42, v47
	v_cmp_lt_u32_e64 s[34:35], v2, v64
	v_or_b32_e32 v2, 43, v47
	v_cmp_lt_u32_e64 s[38:39], v2, v64
	v_or_b32_e32 v2, 48, v47
	v_cmp_lt_u32_e64 s[42:43], v2, v64
	v_or_b32_e32 v2, 49, v47
	v_cmp_lt_u32_e64 s[46:47], v2, v64
	v_or_b32_e32 v2, 50, v47
	v_cmp_lt_u32_e64 s[50:51], v2, v64
	v_or_b32_e32 v2, 51, v47
	v_cmp_lt_u32_e64 s[54:55], v2, v64
	v_or_b32_e32 v2, 56, v47
	v_lshlrev_b32_e32 v6, 16, v38
	v_and_b32_e32 v7, 0xffff0000, v38
	v_lshlrev_b32_e32 v8, 16, v39
	v_and_b32_e32 v9, 0xffff0000, v39
	s_lshl_b32 s3, s84, 2
	v_cmp_lt_u32_e64 s[58:59], v2, v64
	v_or_b32_e32 v2, 57, v47
	v_mov_b32_e32 v16, v5
	v_mov_b32_e32 v17, v5
	v_and_or_b32 v20, v181, 64, v169
	global_store_dwordx4 v[12:13], v[6:9], off offset:128
	s_add_i32 s93, s3, 0
	v_cmp_lt_u32_e64 s[6:7], v47, v64
	v_cmp_lt_u32_e64 s[62:63], v2, v64
	s_lshl_b32 s3, s1, 15
	s_lshl_b32 s1, s1, 2
	v_mov_b32_e32 v2, v5
	v_mov_b32_e32 v3, v5
	v_mov_b32_e32 v6, v5
	v_mov_b32_e32 v7, v5
	v_mov_b32_e32 v8, v5
	v_mov_b32_e32 v9, v5
	v_mov_b32_e32 v10, v5
	v_mov_b32_e32 v11, v5
	v_mov_b32_e32 v12, v5
	v_mov_b32_e32 v13, v5
	v_mov_b32_e32 v14, v5
	v_mov_b32_e32 v15, v5
	v_lshlrev_b32_e32 v173, 2, v20
	v_mov_b64_e32 v[34:35], v[16:17]
	v_mov_b64_e32 v[50:51], v[16:17]
	s_add_i32 s93, s93, 0x20c00
	v_cmp_lt_u32_e64 s[56:57], v56, v64
	v_cmp_lt_u32_e64 s[60:61], v61, v64
	v_cmp_lt_u32_e64 s[64:65], v60, v64
	s_lshl_b32 s95, s2, 13
	s_sub_i32 s96, 0x30000, s3
	s_sub_i32 s97, s2, s1
	s_sub_i32 s1, 0, s1
	v_mov_b32_e32 v52, 0
	s_mov_b32 s33, 28
	v_mov_b64_e32 v[32:33], v[14:15]
	v_mov_b64_e32 v[30:31], v[12:13]
	v_mov_b64_e32 v[28:29], v[10:11]
	v_mov_b64_e32 v[26:27], v[8:9]
	v_mov_b64_e32 v[24:25], v[6:7]
	v_mov_b64_e32 v[22:23], v[4:5]
	v_mov_b64_e32 v[20:21], v[2:3]
	v_mov_b64_e32 v[48:49], v[14:15]
	v_mov_b64_e32 v[46:47], v[12:13]
	v_mov_b64_e32 v[44:45], v[10:11]
	v_mov_b64_e32 v[42:43], v[8:9]
	v_mov_b64_e32 v[40:41], v[6:7]
	v_mov_b64_e32 v[38:39], v[4:5]
	v_mov_b64_e32 v[36:37], v[2:3]
	v_cmp_lt_u32_e64 s[66:67], v54, v64
	v_cmp_lt_u32_e64 s[68:69], v63, v64
	v_cmp_lt_u32_e64 s[70:71], v55, v64
	v_cmp_eq_u32_e64 s[72:73], 0, v53
	s_mov_b64 s[74:75], 0
	s_add_i32 s89, s1, s33
	s_waitcnt lgkmcnt(0)
	s_barrier
	s_branch .LBB0_942

; #define LAS __attribute__((address_space(3)))
; __device__ __forceinline__ unsigned cvtpk(float lo, float hi) { f32x2 v = {lo, hi}; bf16x2_t b = __builtin_convertvector(v, bf16x2_t); return __builtin_bit_cast(unsigned, b); }
; __device__ __forceinline__ void prompt_unit_fox(const Args& a, int l, int b, int h, int qb, LAS unsigned char* lds) {
;     int tid_ = threadIdx.x; asm volatile("" : "+v"(tid_));
;     const int tid = tid_, lane = tid & 63, r32 = lane & 31, hi = lane >> 5, wid = __builtin_amdgcn_readfirstlane(tid >> 6);
;     const int q0 = qb * 256, NP = (q0 + 256) / 128, jd = q0 / 64 + (wid >> 1), jpd = jd >> 1;
;     const bool lateB = wid >= 4;
;     const int col = h * HD;
;     const size_t rowb = (size_t)b * T;
;     const bf16* Kh = (const bf16*)(a.ws + WS_K) + rowb * D + col; const bf16* Vh = (const bf16*)(a.ws + WS_V) + rowb * D + col;
;     const unsigned lds0 = (unsigned)(uintptr_t)lds;
;     const bf16* ksrc = Kh + (size_t)lane * D + wid * 8;
;     const bf16* vsrc = Vh + (size_t)(16 * (wid & 3) + (lane >> 2)) * D + (wid >> 2) * 32 + (lane & 3) * 8;
;     ...
;     ATT_DMA2(NP - 1, 0);
;     { const int idx = tid * 4; if (idx < q0 + 256) { const f32x4 c = *(const f32x4*)((const float*)(a.ws + WS_CKP) + (size_t)(b * 8 + h) * T + idx); *(LAS f32x4*)(lds + F_CK + idx * 4) = c;
; #pragma unroll
;         for (int e = 0; e < 4; ++e) { const float h1 = bf_hi_part(c[e]), r1 = c[e] - h1, h2 = bf_hi_part(r1), r2 = r1 - h2; ((LAS u32x2*)(lds + F_AUG))[idx + e] = (u32x2){cvtpk(h1, h2), cvtpk(r2, -1.0f)}; } } }
;     bf16x8 qr[4];
;     { const bf16* Qw = (const bf16*)(a.ws + WS_Q) + (rowb + q0 + wid * 32 + r32) * D + col;
; #pragma unroll
;       for (int d0 = 0; d0 < 4; ++d0) qr[d0] = *(const bf16x8*)(Qw + d0 * 16 + hi * 8); }
;     const lds_cptr vp0 = (lds_cptr)lds + F_V + ((lane >> 4) & 1) * 32 + (lane & 3) * 8 + (4 * hi + ((lane & 15) >> 2)) * 64;
;     const int ql = 32 * (wid & 1) + r32, qlim = ql + 1;
;     LAS float* wsf = (LAS float*)(lds + F_WSF) + wid * 64;
;     FoxState st; st.m = 0.f; st.l = 0.f; st.mq = (bf16x8){}; st.o[0] = (f32x16){}; st.o[1] = (f32x16){};
;     PairP pp; bool pending = false;
; #pragma unroll
;     for (int i = 0; i < 8; ++i) pp.w[i] = (u32x4){0u, 0u, 0u, 0u};
;     { ConvRegs cv; conv_load(cv, a, rowb + q0 + wid * 32, col, lane); conv_store<0>(cv, a, l, h, rowb + q0 + wid * 32, lane); }
.LBB0_963:
	v_writelane_b32 v242, s16, 32
	s_or_b64 exec, exec, s[2:3]
	s_lshl_b32 s0, s0, 2
	s_ashr_i32 s2, s6, 7
	s_add_i32 s2, s2, s0
	s_ashr_i32 s0, s2, 1
	s_cmp_lt_i32 s1, 4
	s_cselect_b64 s[90:91], -1, 0
	s_lshl_b32 s2, s8, 11
	s_lshl_b32 s3, s1, 5
	s_or_b32 s2, s9, s2
	s_ashr_i32 s8, s3, 31
	s_add_u32 s79, s3, s2
	v_and_b32_e32 v180, 31, v19
	s_addc_u32 s10, s8, 0
	v_or_b32_e32 v168, s79, v180
	v_mov_b32_e32 v169, s10
	v_readlane_b32 s8, v242, 28
	v_lshlrev_b64 v[2:3], 11, v[168:169]
	v_readlane_b32 s9, v242, 29
	v_lshrrev_b32_e32 v21, 5, v20
	s_lshl_b32 s74, s7, 1
	v_lshl_add_u64 v[2:3], s[8:9], 0, v[2:3]
	s_mov_b32 s75, s87
	v_lshl_add_u64 v[2:3], v[2:3], 0, s[74:75]
	v_lshlrev_b32_e32 v174, 4, v21
	v_mov_b32_e32 v175, v5
	v_lshl_add_u64 v[2:3], v[2:3], 0, v[174:175]
	global_load_dwordx4 v[6:9], v[2:3], off
	global_load_dwordx4 v[10:13], v[2:3], off offset:32
	global_load_dwordx4 v[14:17], v[2:3], off offset:64
	global_load_dwordx4 v[116:119], v[2:3], off offset:96
	v_lshlrev_b32_e32 v2, 1, v19
	v_and_b32_e32 v2, 32, v2
	v_add_u32_e32 v3, 0, v2
	v_lshlrev_b32_e32 v2, 2, v21
	v_lshrrev_b32_e32 v4, 2, v19
	v_and_or_b32 v4, v4, 3, v2
	v_lshlrev_b32_e32 v4, 6, v4
	s_and_b32 s2, s6, 0x3fffffc0
	v_add3_u32 v175, v3, v1, v4
	s_lshl_b32 s2, s2, 2
	v_lshrrev_b32_e32 v1, 3, v20
	v_and_or_b32 v3, s3, 32, v180
	s_add_i32 s89, s2, 0
	v_or_b32_e32 v168, s79, v1
	v_readlane_b32 s2, v242, 20
	v_lshlrev_b32_e32 v4, 3, v20
	v_lshlrev_b64 v[176:177], 11, v[168:169]
	v_readlane_b32 s3, v242, 21
	v_readlane_b32 s8, v242, 22
	v_and_b32_e32 v178, 56, v4
	v_lshl_add_u64 v[22:23], s[2:3], 0, v[176:177]
	v_readlane_b32 s9, v242, 23
	v_lshl_add_u64 v[22:23], v[22:23], 0, s[74:75]
	v_mov_b32_e32 v4, v178
	v_lshl_add_u64 v[26:27], s[8:9], 0, v[176:177]
	v_lshl_add_u64 v[22:23], v[22:23], 0, v[4:5]
	v_lshl_add_u64 v[26:27], v[26:27], 0, s[74:75]
	v_or_b32_e32 v34, 0x4000, v176
	v_mov_b32_e32 v35, v177
	global_load_dwordx2 v[24:25], v[22:23], off offset:64
	global_load_dwordx2 v[22:23], v[22:23], off
	v_lshl_add_u64 v[26:27], v[26:27], 0, v[4:5]
	v_lshl_add_u64 v[30:31], s[2:3], 0, v[34:35]
	global_load_dwordx2 v[28:29], v[26:27], off offset:64
	global_load_dwordx2 v[26:27], v[26:27], off
	v_lshl_add_u64 v[30:31], v[30:31], 0, s[74:75]
	v_lshl_add_u64 v[30:31], v[30:31], 0, v[4:5]
	global_load_dwordx2 v[32:33], v[30:31], off offset:64
	global_load_dwordx2 v[30:31], v[30:31], off
	v_lshl_add_u64 v[34:35], s[8:9], 0, v[34:35]
	v_lshl_add_u64 v[34:35], v[34:35], 0, s[74:75]
	v_lshl_add_u64 v[34:35], v[34:35], 0, v[4:5]
	global_load_dwordx2 v[36:37], v[34:35], off offset:64
	global_load_dwordx2 v[34:35], v[34:35], off
	v_or_b32_e32 v42, 0x8000, v176
	v_mov_b32_e32 v43, v177
	v_lshl_add_u64 v[38:39], s[2:3], 0, v[42:43]
	v_lshl_add_u64 v[38:39], v[38:39], 0, s[74:75]
	v_lshl_add_u64 v[38:39], v[38:39], 0, v[4:5]
	global_load_dwordx2 v[40:41], v[38:39], off offset:64
	global_load_dwordx2 v[38:39], v[38:39], off
	v_lshl_add_u64 v[42:43], s[8:9], 0, v[42:43]
	v_lshl_add_u64 v[42:43], v[42:43], 0, s[74:75]
	v_lshl_add_u64 v[42:43], v[42:43], 0, v[4:5]
	global_load_dwordx2 v[44:45], v[42:43], off offset:64
	global_load_dwordx2 v[42:43], v[42:43], off
	v_or_b32_e32 v50, 0xc000, v176
	v_mov_b32_e32 v51, v177
	v_lshl_add_u64 v[46:47], s[2:3], 0, v[50:51]
	v_lshl_add_u64 v[46:47], v[46:47], 0, s[74:75]
	v_lshl_add_u64 v[46:47], v[46:47], 0, v[4:5]
	global_load_dwordx2 v[48:49], v[46:47], off offset:64
	global_load_dwordx2 v[46:47], v[46:47], off
	v_lshl_add_u64 v[50:51], s[8:9], 0, v[50:51]
	v_lshl_add_u64 v[50:51], v[50:51], 0, s[74:75]
	v_lshl_add_u64 v[50:51], v[50:51], 0, v[4:5]
	global_load_dwordx2 v[52:53], v[50:51], off offset:64
	global_load_dwordx2 v[50:51], v[50:51], off
	s_add_i32 s89, s89, 0x1a000
	s_add_u32 s2, s79, 0x10000
	v_writelane_b32 v242, s10, 34
	s_addc_u32 s3, s10, 0
	v_or_b32_e32 v54, s2, v1
	v_mov_b32_e32 v55, s3
	v_readlane_b32 s2, v242, 26
	v_lshlrev_b64 v[54:55], 11, v[54:55]
	v_readlane_b32 s3, v242, 27
	s_lshl_b32 s92, s7, 2
	s_mov_b32 s93, s87
	v_lshl_add_u64 v[56:57], s[2:3], 0, v[54:55]
	v_readlane_b32 s2, v242, 43
	v_readlane_b32 s3, v242, 44
	v_lshl_add_u64 v[56:57], v[56:57], 0, s[92:93]
	v_lshlrev_b32_e32 v4, 1, v178
	v_lshl_add_u64 v[54:55], s[2:3], 0, v[54:55]
	v_lshl_add_u64 v[54:55], v[54:55], 0, s[92:93]
	v_lshl_add_u64 v[58:59], v[56:57], 0, v[4:5]
	v_lshl_add_u64 v[60:61], v[54:55], 0, v[4:5]
	v_or_b32_e32 v4, 32, v2
	v_cmp_gt_u32_e64 s[10:11], v4, v3
	v_or_b32_e32 v4, 33, v2
	v_cmp_gt_u32_e64 s[14:15], v4, v3
	v_or_b32_e32 v4, 2, v2
	v_cmp_gt_u32_e64 s[16:17], v4, v3
	v_or_b32_e32 v4, 34, v2
	v_cmp_gt_u32_e64 s[18:19], v4, v3
	v_or_b32_e32 v4, 3, v2
	v_cmp_gt_u32_e64 s[20:21], v4, v3
	v_or_b32_e32 v4, 35, v2
	v_cmp_gt_u32_e64 s[22:23], v4, v3
	v_or_b32_e32 v4, 8, v2
	s_mov_b64 s[2:3], 0x4000
	v_cmp_gt_u32_e64 s[24:25], v4, v3
	v_or_b32_e32 v4, 40, v2
	v_cmp_gt_u32_e64 s[26:27], v4, v3
	v_or_b32_e32 v4, 9, v2
	v_cmp_gt_u32_e64 s[28:29], v4, v3
	v_or_b32_e32 v4, 41, v2
	v_cmp_gt_u32_e64 s[30:31], v4, v3
	v_or_b32_e32 v4, 10, v2
	v_cmp_gt_u32_e64 s[34:35], v4, v3
	v_or_b32_e32 v4, 42, v2
	v_cmp_gt_u32_e64 s[36:37], v4, v3
	v_or_b32_e32 v4, 11, v2
	v_cmp_gt_u32_e64 s[38:39], v4, v3
	v_or_b32_e32 v4, 43, v2
	v_cmp_gt_u32_e64 s[40:41], v4, v3

; #define LAS __attribute__((address_space(3)))
; __device__ __forceinline__ float bflo(unsigned w) { return __uint_as_float(w << 16); }
; __device__ __forceinline__ float bfhi(unsigned w) { return __uint_as_float(w & 0xffff0000u); }
; __device__ __forceinline__ unsigned cvtpk(float lo, float hi) { f32x2 v = {lo, hi}; bf16x2_t b = __builtin_convertvector(v, bf16x2_t); return __builtin_bit_cast(unsigned, b); }
; __device__ __forceinline__ float bf_hi_part(float x) { return __uint_as_float(cvtpk(x, 0.f) << 16); }
; template <int TYPE>
; __device__ __forceinline__ void conv_store(const ConvRegs& c, const Args& a, int l, int h, size_t rowq, int lane) {
; #pragma unroll
;     for (int i = 0; i < 4; ++i) { const size_t grow = rowq + i * 8 + (lane >> 3);
;         float* ko = a.out + (TYPE == 0 ? O_FKP : O_SKP) + ((size_t)l * MP + grow) * W + h * HD + (lane & 7) * 8;
;         float* vo = a.out + (TYPE == 0 ? O_FVP : O_SVP) + ((size_t)l * MP + grow) * W + h * HD + (lane & 7) * 8;
;         const u32x4 kw = c.k[i], vw = c.v[i];
;         __builtin_nontemporal_store((f32x4){bflo(kw.x), bfhi(kw.x), bflo(kw.y), bfhi(kw.y)}, (f32x4*)ko); __builtin_nontemporal_store((f32x4){bflo(kw.z), bfhi(kw.z), bflo(kw.w), bfhi(kw.w)}, (f32x4*)(ko + 4));
;         __builtin_nontemporal_store((f32x4){bflo(vw.x), bfhi(vw.x), bflo(vw.y), bfhi(vw.y)}, (f32x4*)vo); __builtin_nontemporal_store((f32x4){bflo(vw.z), bfhi(vw.z), bflo(vw.w), bfhi(vw.w)}, (f32x4*)(vo + 4)); }
; }
; __device__ __forceinline__ void prompt_unit_fox(const Args& a, int l, int b, int h, int qb, LAS unsigned char* lds) {
;     ...
;     { const int idx = tid * 4; if (idx < q0 + 256) { const f32x4 c = *(const f32x4*)((const float*)(a.ws + WS_CKP) + (size_t)(b * 8 + h) * T + idx); *(LAS f32x4*)(lds + F_CK + idx * 4) = c;
; #pragma unroll
;         for (int e = 0; e < 4; ++e) { const float h1 = bf_hi_part(c[e]), r1 = c[e] - h1, h2 = bf_hi_part(r1), r2 = r1 - h2; ((LAS u32x2*)(lds + F_AUG))[idx + e] = (u32x2){cvtpk(h1, h2), cvtpk(r2, -1.0f)}; } } }
	s_cmp_lg_u32 s83, 0
	s_cbranch_scc0 .Lck_skip_l1
	s_waitcnt vmcnt(20)
	ds_write_b128 v87, v[90:93]
	v_cvt_pk_bf16_f32 v87, v90, 0
	v_lshlrev_b32_e32 v87, 16, v87
	v_sub_f32_e32 v88, v90, v87
	v_cvt_pk_bf16_f32 v90, v88, 0
	v_lshlrev_b32_e32 v90, 16, v90
	v_cvt_pk_bf16_f32 v94, v87, v90
	v_cvt_pk_bf16_f32 v87, v91, 0
	v_sub_f32_e32 v88, v88, v90
	v_lshlrev_b32_e32 v87, 16, v87
	v_cvt_pk_bf16_f32 v95, v88, -1.0
	v_sub_f32_e32 v88, v91, v87
	v_cvt_pk_bf16_f32 v90, v88, 0
	v_lshlrev_b32_e32 v90, 16, v90
	v_cvt_pk_bf16_f32 v96, v87, v90
	v_cvt_pk_bf16_f32 v87, v92, 0
	v_sub_f32_e32 v88, v88, v90
	v_lshlrev_b32_e32 v87, 16, v87
	v_cvt_pk_bf16_f32 v97, v88, -1.0
	v_sub_f32_e32 v88, v92, v87
	v_cvt_pk_bf16_f32 v90, v88, 0
	v_lshlrev_b32_e32 v90, 16, v90
	v_sub_f32_e32 v88, v88, v90
	v_cvt_pk_bf16_f32 v90, v87, v90
	v_cvt_pk_bf16_f32 v87, v93, 0
	v_lshlrev_b32_e32 v87, 16, v87
	v_cvt_pk_bf16_f32 v91, v88, -1.0
	v_sub_f32_e32 v88, v93, v87
	v_cvt_pk_bf16_f32 v92, v88, 0
	v_lshlrev_b32_e32 v92, 16, v92
	v_sub_f32_e32 v88, v88, v92
	v_cvt_pk_bf16_f32 v92, v87, v92
	v_cvt_pk_bf16_f32 v93, v88, -1.0
	ds_write_b128 v86, v[94:97]
	ds_write_b128 v86, v[90:93] offset:16
.Lck_skip_l1:
	s_waitcnt vmcnt(14)
	v_lshlrev_b32_e32 v54, 16, v22
	v_and_b32_e32 v55, 0xffff0000, v22
	v_lshlrev_b32_e32 v56, 16, v23
	v_and_b32_e32 v57, 0xffff0000, v23
	v_lshlrev_b32_e32 v22, 16, v24
	v_and_b32_e32 v23, 0xffff0000, v24
	v_lshlrev_b32_e32 v24, 16, v25
	v_and_b32_e32 v25, 0xffff0000, v25
	global_store_dwordx4 v[58:59], v[22:25], off offset:128
	v_or_b32_e32 v4, 16, v2
	v_cmp_gt_u32_e64 s[42:43], v4, v3
	s_waitcnt vmcnt(13)
	v_lshlrev_b32_e32 v22, 16, v26
	v_and_b32_e32 v23, 0xffff0000, v26
	v_lshlrev_b32_e32 v24, 16, v27
	v_and_b32_e32 v25, 0xffff0000, v27
	global_store_dwordx4 v[60:61], v[22:25], off
	v_lshl_add_u64 v[26:27], v[58:59], 0, s[2:3]
	v_or_b32_e32 v4, 48, v2
	v_lshlrev_b32_e32 v22, 16, v28
	v_and_b32_e32 v23, 0xffff0000, v28
	v_lshlrev_b32_e32 v24, 16, v29
	v_and_b32_e32 v25, 0xffff0000, v29
	v_lshl_add_u64 v[28:29], v[60:61], 0, s[2:3]
	s_movk_i32 s2, 0x4000
	global_store_dwordx4 v[60:61], v[22:25], off offset:128
	v_cmp_gt_u32_e64 s[44:45], v4, v3
	v_or_b32_e32 v4, 17, v2
	s_waitcnt vmcnt(13)
	v_lshlrev_b32_e32 v22, 16, v30
	v_and_b32_e32 v23, 0xffff0000, v30
	v_add_co_u32_e32 v30, vcc, s2, v58
	v_lshlrev_b32_e32 v24, 16, v31
	v_and_b32_e32 v25, 0xffff0000, v31
	v_addc_co_u32_e32 v31, vcc, 0, v59, vcc
	global_store_dwordx4 v[30:31], v[22:25], off
	v_cmp_gt_u32_e64 s[46:47], v4, v3
	v_or_b32_e32 v4, 49, v2
	v_lshlrev_b32_e32 v22, 16, v32
	v_and_b32_e32 v23, 0xffff0000, v32
	v_lshlrev_b32_e32 v24, 16, v33
	v_and_b32_e32 v25, 0xffff0000, v33
	global_store_dwordx4 v[26:27], v[22:25], off offset:128
	v_add_co_u32_e32 v26, vcc, s2, v60
	s_nop 0
	s_waitcnt vmcnt(13)
	v_lshlrev_b32_e32 v22, 16, v34
	v_and_b32_e32 v23, 0xffff0000, v34
	v_lshlrev_b32_e32 v24, 16, v35
	v_and_b32_e32 v25, 0xffff0000, v35
	v_addc_co_u32_e32 v27, vcc, 0, v61, vcc
	global_store_dwordx4 v[26:27], v[22:25], off
	s_mov_b64 s[2:3], 0x8000
	v_lshl_add_u64 v[26:27], v[58:59], 0, s[2:3]
	v_lshlrev_b32_e32 v22, 16, v36
	v_and_b32_e32 v23, 0xffff0000, v36
	v_lshlrev_b32_e32 v24, 16, v37
	v_and_b32_e32 v25, 0xffff0000, v37
	global_store_dwordx4 v[28:29], v[22:25], off offset:128
	v_lshl_add_u64 v[28:29], v[60:61], 0, s[2:3]
	s_mov_b32 s2, 0x8000
	v_add_co_u32_e32 v30, vcc, s2, v58
	s_waitcnt vmcnt(13)
	v_lshlrev_b32_e32 v22, 16, v38
	v_and_b32_e32 v23, 0xffff0000, v38
	v_lshlrev_b32_e32 v24, 16, v39
	v_and_b32_e32 v25, 0xffff0000, v39
	v_addc_co_u32_e32 v31, vcc, 0, v59, vcc
	global_store_dwordx4 v[30:31], v[22:25], off
	v_cmp_gt_u32_e64 s[48:49], v4, v3
	v_or_b32_e32 v4, 18, v2
	v_lshlrev_b32_e32 v22, 16, v40
	v_and_b32_e32 v23, 0xffff0000, v40
	v_lshlrev_b32_e32 v24, 16, v41
	v_and_b32_e32 v25, 0xffff0000, v41
	global_store_dwordx4 v[26:27], v[22:25], off offset:128
	v_add_co_u32_e32 v26, vcc, s2, v60
	v_cmp_gt_u32_e64 s[50:51], v4, v3
	v_or_b32_e32 v4, 50, v2
	s_waitcnt vmcnt(13)
; #define LAS __attribute__((address_space(3)))
; __device__ __forceinline__ float bflo(unsigned w) { return __uint_as_float(w << 16); }
; __device__ __forceinline__ float bfhi(unsigned w) { return __uint_as_float(w & 0xffff0000u); }
; #define ATT_WAIT_BAR() asm volatile("s_waitcnt vmcnt(0) lgkmcnt(0)\n\ts_barrier" ::: "memory")
; template <int TYPE>
; __device__ __forceinline__ void conv_store(const ConvRegs& c, const Args& a, int l, int h, size_t rowq, int lane) {
; #pragma unroll
;     for (int i = 0; i < 4; ++i) { const size_t grow = rowq + i * 8 + (lane >> 3);
;         float* ko = a.out + (TYPE == 0 ? O_FKP : O_SKP) + ((size_t)l * MP + grow) * W + h * HD + (lane & 7) * 8;
;         float* vo = a.out + (TYPE == 0 ? O_FVP : O_SVP) + ((size_t)l * MP + grow) * W + h * HD + (lane & 7) * 8;
;         const u32x4 kw = c.k[i], vw = c.v[i];
;         __builtin_nontemporal_store((f32x4){bflo(kw.x), bfhi(kw.x), bflo(kw.y), bfhi(kw.y)}, (f32x4*)ko); __builtin_nontemporal_store((f32x4){bflo(kw.z), bfhi(kw.z), bflo(kw.w), bfhi(kw.w)}, (f32x4*)(ko + 4));
;         __builtin_nontemporal_store((f32x4){bflo(vw.x), bfhi(vw.x), bflo(vw.y), bfhi(vw.y)}, (f32x4*)vo); __builtin_nontemporal_store((f32x4){bflo(vw.z), bfhi(vw.z), bflo(vw.w), bfhi(vw.w)}, (f32x4*)(vo + 4)); }
; }
; __device__ __forceinline__ void prompt_unit_fox(const Args& a, int l, int b, int h, int qb, LAS unsigned char* lds) {
;     ...
;     const lds_cptr vp0 = (lds_cptr)lds + F_V + ((lane >> 4) & 1) * 32 + (lane & 3) * 8 + (4 * hi + ((lane & 15) >> 2)) * 64;
;     const int ql = 32 * (wid & 1) + r32, qlim = ql + 1;
;     LAS float* wsf = (LAS float*)(lds + F_WSF) + wid * 64;
;     FoxState st; st.m = 0.f; st.l = 0.f; st.mq = (bf16x8){}; st.o[0] = (f32x16){}; st.o[1] = (f32x16){};
;     PairP pp; bool pending = false;
; #pragma unroll
;     for (int i = 0; i < 8; ++i) pp.w[i] = (u32x4){0u, 0u, 0u, 0u};
;     { ConvRegs cv; conv_load(cv, a, rowb + q0 + wid * 32, col, lane); conv_store<0>(cv, a, l, h, rowb + q0 + wid * 32, lane); }
;     int slot = 0, pslot = 0;
;     ...
;         ATT_WAIT_BAR();
	v_lshlrev_b32_e32 v22, 16, v42
	v_and_b32_e32 v23, 0xffff0000, v42
	v_lshlrev_b32_e32 v24, 16, v43
	v_and_b32_e32 v25, 0xffff0000, v43
	v_addc_co_u32_e32 v27, vcc, 0, v61, vcc
	v_cmp_gt_u32_e64 s[52:53], v4, v3
	v_or_b32_e32 v4, 19, v2
	global_store_dwordx4 v[26:27], v[22:25], off
	s_mov_b64 s[2:3], 0xc000
	v_cmp_gt_u32_e64 s[54:55], v4, v3
	v_lshlrev_b32_e32 v22, 16, v44
	v_and_b32_e32 v23, 0xffff0000, v44
	v_lshlrev_b32_e32 v24, 16, v45
	v_and_b32_e32 v25, 0xffff0000, v45
	v_or_b32_e32 v4, 51, v2
	global_store_dwordx4 v[28:29], v[22:25], off offset:128
	v_lshl_add_u64 v[26:27], v[58:59], 0, s[2:3]
	v_lshl_add_u64 v[28:29], v[60:61], 0, s[2:3]
	s_mov_b32 s2, 0xc000
	v_cmp_gt_u32_e64 s[56:57], v4, v3
	v_or_b32_e32 v4, 24, v2
	v_add_co_u32_e32 v30, vcc, s2, v58
	v_cmp_gt_u32_e64 s[58:59], v4, v3
	v_or_b32_e32 v4, 56, v2
	s_waitcnt vmcnt(13)
	v_lshlrev_b32_e32 v22, 16, v46
	v_and_b32_e32 v23, 0xffff0000, v46
	v_lshlrev_b32_e32 v24, 16, v47
	v_and_b32_e32 v25, 0xffff0000, v47
	v_addc_co_u32_e32 v31, vcc, 0, v59, vcc
	v_cmp_gt_u32_e64 s[60:61], v4, v3
	v_or_b32_e32 v4, 25, v2
	global_store_dwordx4 v[30:31], v[22:25], off
	v_cmp_gt_u32_e64 s[62:63], v4, v3
	v_or_b32_e32 v4, 57, v2
	v_lshlrev_b32_e32 v22, 16, v48
	v_and_b32_e32 v23, 0xffff0000, v48
	v_lshlrev_b32_e32 v24, 16, v49
	v_and_b32_e32 v25, 0xffff0000, v49
	global_store_dwordx4 v[26:27], v[22:25], off offset:128
	v_add_co_u32_e32 v26, vcc, s2, v60
	s_add_i32 s2, 0, 0x18000
	v_cmp_gt_u32_e64 s[64:65], v4, v3
	v_or_b32_e32 v4, 26, v2
	s_waitcnt vmcnt(13)
	v_lshlrev_b32_e32 v22, 16, v50
	v_and_b32_e32 v23, 0xffff0000, v50
	v_lshlrev_b32_e32 v24, 16, v51
	v_and_b32_e32 v25, 0xffff0000, v51
	v_addc_co_u32_e32 v27, vcc, 0, v61, vcc
	v_add_u32_e32 v186, s2, v174
	s_add_i32 s2, 0, 0x1a800
	v_cmp_gt_u32_e64 s[66:67], v4, v3
	v_or_b32_e32 v4, 58, v2
	v_mov_b32_e32 v66, v5
	v_mov_b32_e32 v67, v5
	global_store_dwordx4 v[58:59], v[54:57], off
	global_store_dwordx4 v[26:27], v[22:25], off
	s_bitcmp1_b32 s6, 7
	v_cmp_gt_u32_e64 s[6:7], 32, v20
	v_lshlrev_b32_e32 v22, 16, v52
	v_and_b32_e32 v23, 0xffff0000, v52
	v_lshlrev_b32_e32 v24, 16, v53
	v_and_b32_e32 v25, 0xffff0000, v53
	v_cmp_gt_u32_e64 s[8:9], v2, v3
	v_cmp_lt_u32_e64 s[12:13], v2, v3
	v_cmp_gt_u32_e64 s[68:69], v4, v3
	v_or_b32_e32 v4, 27, v2
	v_or_b32_e32 v2, 59, v2
	v_mov_b32_e32 v52, v5
	v_mov_b32_e32 v53, v5
	v_mov_b32_e32 v54, v5
	v_mov_b32_e32 v55, v5
	v_mov_b32_e32 v56, v5
	v_mov_b32_e32 v57, v5
	v_mov_b32_e32 v58, v5
	v_mov_b32_e32 v59, v5
	v_mov_b32_e32 v60, v5
	v_mov_b32_e32 v61, v5
	v_mov_b32_e32 v62, v5
	v_mov_b32_e32 v63, v5
	v_mov_b32_e32 v64, v5
	v_mov_b32_e32 v65, v5
	v_mov_b64_e32 v[82:83], v[66:67]
	s_mov_b32 s75, 0
	v_lshl_add_u32 v188, v180, 3, s2
	s_cselect_b64 s[94:95], -1, 0
	v_lshlrev_b32_e32 v182, 10, v21
	v_lshlrev_b32_e32 v189, 4, v180
	v_cndmask_b32_e64 v122, 0, v183, s[6:7]
	v_cndmask_b32_e64 v121, 0, -1.0, s[6:7]
	v_mov_b32_e32 v120, v5
	v_mov_b32_e32 v123, v5
	v_cmp_gt_u32_e64 s[70:71], v4, v3
	v_cmp_gt_u32_e64 s[72:73], v2, v3
	v_lshl_add_u32 v184, v180, 2, s89
	v_mov_b32_e32 v156, v5
	v_mov_b32_e32 v157, v5
	v_mov_b32_e32 v158, v5
	v_mov_b32_e32 v159, v5
	v_mov_b32_e32 v192, 0
	s_mov_b64 s[2:3], 0
	v_mov_b32_e32 v124, 0
	v_mov_b32_e32 v125, 0
	v_mov_b32_e32 v126, 0
	v_mov_b32_e32 v127, 0
	v_mov_b32_e32 v128, 0
	v_mov_b32_e32 v129, 0
	v_mov_b32_e32 v130, 0
	v_mov_b32_e32 v131, 0
	v_mov_b32_e32 v132, 0
	v_mov_b32_e32 v133, 0
	v_mov_b32_e32 v134, 0
	v_mov_b32_e32 v135, 0
	v_mov_b32_e32 v136, 0
	v_mov_b32_e32 v137, 0
	v_mov_b32_e32 v138, 0
	v_mov_b32_e32 v139, 0
	v_mov_b32_e32 v140, 0
	v_mov_b32_e32 v141, 0
	v_mov_b32_e32 v142, 0
	v_mov_b32_e32 v143, 0
	v_mov_b32_e32 v144, 0
	v_mov_b32_e32 v145, 0
	v_mov_b32_e32 v146, 0
	v_mov_b32_e32 v147, 0
	v_mov_b32_e32 v148, 0
	v_mov_b32_e32 v149, 0
	v_mov_b32_e32 v150, 0
	v_mov_b32_e32 v151, 0
	v_mov_b32_e32 v152, 0
	v_mov_b32_e32 v153, 0
	v_mov_b32_e32 v154, 0
	v_mov_b32_e32 v155, 0
	v_cndmask_b32_e64 v2, 0, v185, s[6:7]
	s_mov_b32 s93, 0
	v_mov_b64_e32 v[80:81], v[64:65]
	v_mov_b64_e32 v[78:79], v[62:63]
	v_mov_b64_e32 v[76:77], v[60:61]
	v_mov_b64_e32 v[74:75], v[58:59]
	v_mov_b64_e32 v[72:73], v[56:57]
	v_mov_b64_e32 v[70:71], v[54:55]
	v_mov_b64_e32 v[68:69], v[52:53]
	v_mov_b32_e32 v193, 0
	global_store_dwordx4 v[28:29], v[22:25], off offset:128
	s_waitcnt vmcnt(16) lgkmcnt(0)
	s_barrier
	v_mov_b64_e32 v[20:21], 0
	v_mov_b64_e32 v[22:23], 0
	v_mov_b64_e32 v[24:25], 0
	v_mov_b64_e32 v[26:27], 0
	v_mov_b64_e32 v[28:29], 0
	v_mov_b64_e32 v[30:31], 0
	v_mov_b64_e32 v[32:33], 0
	v_mov_b64_e32 v[34:35], 0
	v_mov_b64_e32 v[36:37], 0
	v_mov_b64_e32 v[38:39], 0
	v_mov_b64_e32 v[40:41], 0
	v_mov_b64_e32 v[42:43], 0
	v_mov_b64_e32 v[44:45], 0
	v_mov_b64_e32 v[46:47], 0
	v_mov_b64_e32 v[48:49], 0
	v_mov_b64_e32 v[50:51], 0
	s_branch .Lfox_top_l1
